# v68 with half-size converter items (64k x 8n per interval, spread over intervals 18..62) to stay inside the helper's slack
# speedup vs baseline: 1.0078x; 1.0078x over previous
.Lcv_noscale:
	s_nop 1
	v_mov_b32_dpp v84, v242 quad_perm:[1,0,3,2] row_mask:0xf bank_mask:0xf
	v_mov_b32_dpp v85, v243 quad_perm:[1,0,3,2] row_mask:0xf bank_mask:0xf
	v_mov_b32_dpp v89, v244 quad_perm:[1,0,3,2] row_mask:0xf bank_mask:0xf
	v_mov_b32_dpp v90, v245 quad_perm:[1,0,3,2] row_mask:0xf bank_mask:0xf
	v_mov_b32_dpp v94, v246 quad_perm:[1,0,3,2] row_mask:0xf bank_mask:0xf
	v_mov_b32_dpp v95, v247 quad_perm:[1,0,3,2] row_mask:0xf bank_mask:0xf
	v_mov_b32_dpp v99, v248 quad_perm:[1,0,3,2] row_mask:0xf bank_mask:0xf
	v_mov_b32_dpp v100, v249 quad_perm:[1,0,3,2] row_mask:0xf bank_mask:0xf
	v_cndmask_b32_e64 v86, v85, v242, s[62:63]
	v_cndmask_b32_e64 v87, v243, v84, s[62:63]
	v_cvt_pk_bf16_f32 v88, v86, v87
	v_cndmask_b32_e64 v91, v90, v244, s[62:63]
	v_cndmask_b32_e64 v92, v245, v89, s[62:63]
	v_cvt_pk_bf16_f32 v93, v91, v92
	v_cndmask_b32_e64 v96, v95, v246, s[62:63]
	v_cndmask_b32_e64 v97, v247, v94, s[62:63]
	v_cvt_pk_bf16_f32 v98, v96, v97
	v_cndmask_b32_e64 v101, v100, v248, s[62:63]
	v_cndmask_b32_e64 v102, v249, v99, s[62:63]
	v_cvt_pk_bf16_f32 v103, v101, v102
	global_store_dword v232, v88, s[50:51]
	s_add_u32 s50, s50, s52
	s_addc_u32 s51, s51, 0
	global_store_dword v232, v93, s[50:51]
	s_add_u32 s50, s50, s52
	s_addc_u32 s51, s51, 0
	global_store_dword v232, v98, s[50:51]
	s_add_u32 s50, s50, s52
	s_addc_u32 s51, s51, 0
	global_store_dword v232, v103, s[50:51]
.Lcv_noproc:
	s_mov_b32 s34, 0
	s_sub_u32 s54, s12, 18
	s_cmp_lt_u32 s54, 0x40
	s_cbranch_scc0 .Lcv_noitem
	s_lshl_b32 s54, s54, 10
	s_lshl_b32 s53, s8, 2
	s_add_i32 s53, s53, s11
	s_add_i32 s53, s53, -4
	s_add_i32 s54, s54, s53
	s_mov_b32 s55, 0x7000
	s_cmp_eq_u32 s30, 0
	s_cselect_b32 s55, 0xb200, s55
	s_cmp_lt_u32 s54, s55
	s_cbranch_scc0 .Lcv_noitem
	s_lshl_b32 s61, s30, 12
	s_cmp_lt_u32 s54, 0x2600
	s_cbranch_scc0 .Lcv_j1
	v_readlane_b32 s58, v254, 55
	v_readlane_b32 s59, v254, 56
	v_readlane_b32 s6, v254, 53
	v_readlane_b32 s7, v254, 54
	s_mul_i32 s4, s30, 0x2100000
	s_mov_b32 s60, 0x1080000
	s_mov_b32 s57, 3
	s_nop 1
	s_add_u32 s6, s6, s61
	s_addc_u32 s7, s7, 0
	s_branch .Lcv_jsel
.Lcv_j1:
	s_cmp_lt_u32 s54, 0x2e00
	s_cbranch_scc0 .Lcv_j2
	s_sub_u32 s54, s54, 0x2600
	v_readlane_b32 s58, v255, 17
	v_readlane_b32 s59, v255, 18
	s_lshl_b32 s4, s30, 22
	s_mov_b32 s60, 0x2100000
	s_mov_b32 s57, 0
	s_branch .Lcv_jsel
.Lcv_j2:
	s_cmp_lt_u32 s54, 0x5a00
	s_cbranch_scc0 .Lcv_j3
	s_sub_u32 s54, s54, 0x2e00
	s_mov_b64 s[58:59], s[22:23]
	s_mul_i32 s4, s30, 0x1600000
	s_add_u32 s6, s20, s61
	s_addc_u32 s7, s21, 0
	s_mov_b32 s60, 0x2300000
	s_mov_b32 s57, 1
	s_branch .Lcv_jsel
.Lcv_j3:
	s_cmp_lt_u32 s54, 0x7000
	s_cbranch_scc0 .Lcv_j4
	s_sub_u32 s54, s54, 0x5a00
	s_mov_b64 s[58:59], s[24:25]
	s_mul_i32 s4, s30, 0xb00000
	s_mov_b32 s60, 0x2e00000
	s_mov_b32 s57, 2
	s_branch .Lcv_jsel
.Lcv_j4:
	s_cmp_lt_u32 s54, 0x9c00
	s_cbranch_scc0 .Lcv_j5
	s_sub_u32 s54, s54, 0x7000
	v_readlane_b32 s58, v254, 49
	v_readlane_b32 s59, v254, 50
	v_readlane_b32 s6, v254, 47
	v_readlane_b32 s7, v254, 48
	s_mov_b32 s4, 0x1600000
	s_mov_b32 s60, 0
	s_mov_b32 s57, 1
	s_nop 1
	s_add_u32 s6, s6, 0x1000
	s_addc_u32 s7, s7, 0
	s_branch .Lcv_jsel
.Lcv_j5:
	s_cmp_lt_u32 s54, 0xb200
	s_cbranch_scc0 .Lcv_j6
	s_sub_u32 s54, s54, 0x9c00
	v_readlane_b32 s58, v254, 51
	v_readlane_b32 s59, v254, 52
	s_mov_b32 s4, 0xb00000
	s_mov_b32 s60, 0xb00000
	s_mov_b32 s57, 2
	s_branch .Lcv_jsel
.Lcv_j6:
	s_sub_u32 s54, s54, 0xb200
	v_readlane_b32 s58, v254, 55
	v_readlane_b32 s59, v254, 56
	v_readlane_b32 s6, v254, 53
	v_readlane_b32 s7, v254, 54
	s_mov_b32 s4, 0x2100000
	s_mov_b32 s60, 0x1080000
	s_mov_b32 s57, 4
	s_nop 1
	s_add_u32 s6, s6, 0x1000
	s_addc_u32 s7, s7, 0
.Lcv_jsel:
	s_nop 1
	s_add_u32 s58, s58, s4
	s_addc_u32 s59, s59, 0
	s_cmp_eq_u32 s57, 1
	s_cbranch_scc1 .Lcv_shb
	s_cmp_eq_u32 s57, 3
	s_cbranch_scc1 .Lcv_shd
	s_cmp_eq_u32 s57, 4
	s_cbranch_scc1 .Lcv_she
	s_and_b32 s55, s54, 127
	s_lshr_b32 s56, s54, 7
	s_lshl_b32 s0, s55, 3
	s_mov_b32 s1, 0x1000
	s_mov_b32 s5, 0xb00
	s_cmp_eq_u32 s57, 0
	s_cselect_b32 s5, 0x400, s5
	s_mov_b32 s35, 0
	s_branch .Lcv_shdone
.Lcv_shb:
	s_lshr_b32 s56, s54, 6
	s_mul_i32 s56, s56, 0xba2f
	s_lshr_b32 s56, s56, 19
	s_mul_i32 s55, s56, 0x2c0
	s_sub_u32 s55, s54, s55
	s_lshl_b32 s0, s55, 3
	s_lshr_b32 s1, s0, 8
	s_lshl_b32 s1, s1, 7
	s_and_b32 s5, s0, 0x7f
	s_add_i32 s1, s1, s5
	s_and_b32 s5, s0, 0x80
	s_cmp_lg_u32 s5, 0
	s_cselect_b32 s5, 0xb00, 0
	s_add_i32 s0, s1, s5
	s_mov_b32 s1, 0x5800
	s_mov_b32 s5, 0x400
	s_mov_b32 s35, 1
	s_branch .Lcv_shdone
.Lcv_shd:
	s_lshr_b32 s56, s54, 5
	s_mul_i32 s56, s56, 0xd795
	s_lshr_b32 s56, s56, 20
	s_mul_i32 s55, s56, 0x260
	s_sub_u32 s55, s54, s55
	s_add_i32 s55, s55, 0x1c0
	s_branch .Lcv_m2
.Lcv_she:
	s_lshr_b32 s56, s54, 6
	s_mul_i32 s56, s56, 0x12493
	s_lshr_b32 s56, s56, 19
	s_mul_i32 s55, s56, 0x1c0
	s_sub_u32 s55, s54, s55
.Lcv_m2:
	s_lshl_b32 s0, s55, 3
	s_cmp_lt_u32 s0, 0xd00
	s_cbranch_scc1 .Lcv_m2done
	s_sub_u32 s1, s0, 0xd00
	s_lshr_b32 s4, s1, 8
	s_and_b32 s5, s1, 0xff
	s_cmp_lt_u32 s4, 4
	s_cbranch_scc0 .Lcv_m2b
	s_lshl_b32 s0, s4, 8
	s_add_i32 s0, s0, s5
	s_add_i32 s0, s0, 0x1900
	s_branch .Lcv_m2done

.Lcv_shdone:
	s_lshl_b32 s14, s56, 6
	s_mul_i32 s4, s14, s1
	s_lshl_b32 s0, s0, 2
	s_add_i32 s4, s4, s0
	s_add_u32 s58, s58, s4
	s_addc_u32 s59, s59, 0
	v_mul_u32_u24_e32 v84, s1, v231
	global_load_dwordx4 v[242:245], v84, s[58:59]
	global_load_dwordx4 v[246:249], v84, s[58:59] offset:16
	s_cmp_eq_u32 s35, 0
	s_cbranch_scc1 .Lcv_nosl
	s_lshl_b32 s4, s14, 2
	s_add_u32 s6, s6, s4
	s_addc_u32 s7, s7, 0
	global_load_dword v223, v50, s[6:7]
.Lcv_nosl:
	s_lshl_b32 s4, s55, 3
	s_mul_i32 s4, s4, s5
	s_add_i32 s4, s4, s14
	s_lshl_b32 s4, s4, 1
	s_add_u32 s50, s86, s60
	s_addc_u32 s51, s87, 0
	s_add_u32 s50, s50, s4
	s_addc_u32 s51, s51, 0
	s_lshl_b32 s52, s5, 2
	s_lshl_b32 s4, s5, 1
	v_mul_u32_u24_e32 v232, s4, v51
	v_add_u32_e32 v232, v232, v233
	s_mov_b32 s34, 1

.LBB0_606:
	s_and_b64 vcc, exec, s[0:1]
	s_cbranch_vccz .LBB0_508
	s_waitcnt vmcnt(0)
	v_lshrrev_b32_e32 v90, 4, v241
	v_bfe_u32 v91, v241, 3, 1
	v_and_b32_e32 v86, 15, v241
	v_lshlrev_b32_e32 v90, 1, v90
	v_lshlrev_b32_e32 v86, 4, v86
	v_add_u32_e32 v92, v90, v91
	v_xor_b32_e32 v91, 1, v91
	v_add_u32_e32 v93, v90, v91
	s_lshl_b32 s0, s10, 5
	v_lshlrev_b32_e32 v89, 2, v92
	v_add_u32_e32 v92, s0, v92
	v_add_u32_e32 v93, s0, v93
	v_add_u32_e32 v89, 0x18000, v89
	v_lshlrev_b32_e32 v87, 2, v92
	v_lshlrev_b32_e32 v88, 2, v93
	v_mov_b32_e32 v0, 0
	v_mov_b32_e32 v1, 0
	v_mov_b32_e32 v2, 0
	v_mov_b32_e32 v3, 0
	v_mov_b32_e32 v4, 0
	v_mov_b32_e32 v5, 0
	v_mov_b32_e32 v6, 0
	v_mov_b32_e32 v7, 0
	s_waitcnt lgkmcnt(0)
	s_barrier
	s_mov_b32 s4, 0
.Lrec_chunk:
	s_and_b32 s0, s4, 1
	s_mul_i32 s1, s0, 0xc000
	s_lshl_b32 s5, s0, 8
	v_add_u32_e32 v80, s1, v86
	v_add_u32_e32 v81, s1, v87
	v_add_u32_e32 v82, s1, v88
	s_add_i32 s5, s5, 0x1a100
	s_lshl_b32 s0, s0, 12
	v_mov_b32_e32 v83, s5
	v_add_u32_e32 v84, s0, v89
	ds_read_b128 v[12:15], v80 offset:768
	ds_read_b128 v[16:19], v80 offset:0
	ds_read_b128 v[20:23], v80 offset:256
	ds_read_b128 v[24:27], v80 offset:512
	ds_read_b128 v[28:31], v80 offset:1024
	ds_read_b32 v32, v81 offset:1280
	ds_read_b32 v33, v82 offset:1280
	s_waitcnt lgkmcnt(5)
	v_pk_mul_f32 v[8:9], v[0:1], v[12:13] op_sel_hi:[1,0]
	v_pk_mul_f32 v[10:11], v[0:1], v[16:17] op_sel_hi:[1,0]
	ds_read_b128 v[40:43], v80 offset:2304
	v_pk_fma_f32 v[8:9], v[2:3], v[12:13], v[8:9] op_sel:[0,1,0]
	v_pk_fma_f32 v[10:11], v[2:3], v[16:17], v[10:11] op_sel:[0,1,0]
	ds_read_b128 v[44:47], v80 offset:1536
	v_pk_fma_f32 v[8:9], v[4:5], v[14:15], v[8:9] op_sel_hi:[1,0,1]
	v_pk_fma_f32 v[10:11], v[4:5], v[18:19], v[10:11] op_sel_hi:[1,0,1]
	ds_read_b128 v[48:51], v80 offset:1792
	v_pk_fma_f32 v[8:9], v[6:7], v[14:15], v[8:9] op_sel:[0,1,0]
	v_pk_fma_f32 v[10:11], v[6:7], v[18:19], v[10:11] op_sel:[0,1,0]
	ds_read_b128 v[52:55], v80 offset:2048
	v_add_f32_dpp v74, v9, v8 row_ror:8 row_mask:0xf bank_mask:0xf bound_ctrl:1
	v_add_f32_dpp v75, v11, v10 row_ror:8 row_mask:0xf bank_mask:0xf bound_ctrl:1
	ds_read_b128 v[56:59], v80 offset:2560
	v_add_f32_dpp v74, v74, v74 quad_perm:[1,0,3,2] row_mask:0xf bank_mask:0xf bound_ctrl:1
	v_add_f32_dpp v75, v75, v75 quad_perm:[1,0,3,2] row_mask:0xf bank_mask:0xf bound_ctrl:1
	ds_read_b32 v60, v81 offset:2816
	v_add_f32_dpp v74, v74, v74 quad_perm:[2,3,0,1] row_mask:0xf bank_mask:0xf bound_ctrl:1
	v_add_f32_dpp v75, v75, v75 quad_perm:[2,3,0,1] row_mask:0xf bank_mask:0xf bound_ctrl:1
	ds_read_b32 v61, v82 offset:2816
	v_add_f32_dpp v76, v74, v74 row_half_mirror row_mask:0xf bank_mask:0xf bound_ctrl:1
	v_add_f32_dpp v36, v75, v75 row_half_mirror row_mask:0xf bank_mask:0xf bound_ctrl:1
	s_nop 0
	v_mov_b32_dpp v77, v76 row_ror:8 row_mask:0xf bank_mask:0xf bound_ctrl:1
	s_waitcnt lgkmcnt(7)
	v_pk_mul_f32 v[66:67], v[76:77], v[28:29] op_sel_hi:[1,0]
	v_pk_mul_f32 v[68:69], v[76:77], v[28:29] op_sel:[0,1]
	v_pk_mul_f32 v[70:71], v[76:77], v[30:31] op_sel_hi:[1,0]
	v_pk_mul_f32 v[72:73], v[76:77], v[30:31] op_sel:[0,1]
	v_pk_fma_f32 v[66:67], v[32:33], v[24:25], v[66:67] op_sel_hi:[1,0,1]
	v_pk_fma_f32 v[68:69], v[32:33], v[24:25], v[68:69] op_sel:[0,1,0]
	v_pk_fma_f32 v[70:71], v[32:33], v[26:27], v[70:71] op_sel_hi:[1,0,1]
	v_pk_fma_f32 v[72:73], v[32:33], v[26:27], v[72:73] op_sel:[0,1,0]
	v_pk_fma_f32 v[0:1], v[0:1], v[20:21], v[66:67] op_sel_hi:[1,0,1]
	v_pk_fma_f32 v[2:3], v[2:3], v[20:21], v[68:69] op_sel:[0,1,0]
	v_pk_fma_f32 v[4:5], v[4:5], v[22:23], v[70:71] op_sel_hi:[1,0,1]
	v_pk_fma_f32 v[6:7], v[6:7], v[22:23], v[72:73] op_sel:[0,1,0]
	ds_write_b32 v84, v36 offset:0
	ds_write_b32 v84, v76 offset:12288
	s_waitcnt lgkmcnt(7)
	v_pk_mul_f32 v[8:9], v[0:1], v[40:41] op_sel_hi:[1,0]
	v_pk_mul_f32 v[10:11], v[0:1], v[44:45] op_sel_hi:[1,0]
	ds_read_b128 v[12:15], v80 offset:3840
	v_pk_fma_f32 v[8:9], v[2:3], v[40:41], v[8:9] op_sel:[0,1,0]
	v_pk_fma_f32 v[10:11], v[2:3], v[44:45], v[10:11] op_sel:[0,1,0]
	ds_read_b128 v[16:19], v80 offset:3072
	v_pk_fma_f32 v[8:9], v[4:5], v[42:43], v[8:9] op_sel_hi:[1,0,1]
	v_pk_fma_f32 v[10:11], v[4:5], v[46:47], v[10:11] op_sel_hi:[1,0,1]
	ds_read_b128 v[20:23], v80 offset:3328
	v_pk_fma_f32 v[8:9], v[6:7], v[42:43], v[8:9] op_sel:[0,1,0]
	v_pk_fma_f32 v[10:11], v[6:7], v[46:47], v[10:11] op_sel:[0,1,0]
	ds_read_b128 v[24:27], v80 offset:3584
	v_add_f32_dpp v74, v9, v8 row_ror:8 row_mask:0xf bank_mask:0xf bound_ctrl:1
	v_add_f32_dpp v75, v11, v10 row_ror:8 row_mask:0xf bank_mask:0xf bound_ctrl:1
	ds_read_b128 v[28:31], v80 offset:4096
	v_add_f32_dpp v74, v74, v74 quad_perm:[1,0,3,2] row_mask:0xf bank_mask:0xf bound_ctrl:1
	v_add_f32_dpp v75, v75, v75 quad_perm:[1,0,3,2] row_mask:0xf bank_mask:0xf bound_ctrl:1
	ds_read_b32 v32, v81 offset:4352
	v_add_f32_dpp v74, v74, v74 quad_perm:[2,3,0,1] row_mask:0xf bank_mask:0xf bound_ctrl:1
	v_add_f32_dpp v75, v75, v75 quad_perm:[2,3,0,1] row_mask:0xf bank_mask:0xf bound_ctrl:1
	ds_read_b32 v33, v82 offset:4352
	v_add_f32_dpp v76, v74, v74 row_half_mirror row_mask:0xf bank_mask:0xf bound_ctrl:1
	v_add_f32_dpp v64, v75, v75 row_half_mirror row_mask:0xf bank_mask:0xf bound_ctrl:1
	s_nop 0
	v_mov_b32_dpp v77, v76 row_ror:8 row_mask:0xf bank_mask:0xf bound_ctrl:1
	s_waitcnt lgkmcnt(9)
	v_pk_mul_f32 v[66:67], v[76:77], v[56:57] op_sel_hi:[1,0]
	v_pk_mul_f32 v[68:69], v[76:77], v[56:57] op_sel:[0,1]
	v_pk_mul_f32 v[70:71], v[76:77], v[58:59] op_sel_hi:[1,0]
	v_pk_mul_f32 v[72:73], v[76:77], v[58:59] op_sel:[0,1]
	v_pk_fma_f32 v[66:67], v[60:61], v[52:53], v[66:67] op_sel_hi:[1,0,1]
	v_pk_fma_f32 v[68:69], v[60:61], v[52:53], v[68:69] op_sel:[0,1,0]
	v_pk_fma_f32 v[70:71], v[60:61], v[54:55], v[70:71] op_sel_hi:[1,0,1]
	v_pk_fma_f32 v[72:73], v[60:61], v[54:55], v[72:73] op_sel:[0,1,0]
	v_pk_fma_f32 v[0:1], v[0:1], v[48:49], v[66:67] op_sel_hi:[1,0,1]
	v_pk_fma_f32 v[2:3], v[2:3], v[48:49], v[68:69] op_sel:[0,1,0]
	v_pk_fma_f32 v[4:5], v[4:5], v[50:51], v[70:71] op_sel_hi:[1,0,1]
	v_pk_fma_f32 v[6:7], v[6:7], v[50:51], v[72:73] op_sel:[0,1,0]
	ds_write_b32 v84, v64 offset:128
	ds_write_b32 v84, v76 offset:12416
	s_waitcnt lgkmcnt(7)
	v_pk_mul_f32 v[8:9], v[0:1], v[12:13] op_sel_hi:[1,0]
	v_pk_mul_f32 v[10:11], v[0:1], v[16:17] op_sel_hi:[1,0]
	ds_read_b128 v[40:43], v80 offset:5376
	v_pk_fma_f32 v[8:9], v[2:3], v[12:13], v[8:9] op_sel:[0,1,0]
	v_pk_fma_f32 v[10:11], v[2:3], v[16:17], v[10:11] op_sel:[0,1,0]
	ds_read_b128 v[44:47], v80 offset:4608
	v_pk_fma_f32 v[8:9], v[4:5], v[14:15], v[8:9] op_sel_hi:[1,0,1]
	v_pk_fma_f32 v[10:11], v[4:5], v[18:19], v[10:11] op_sel_hi:[1,0,1]
	ds_read_b128 v[48:51], v80 offset:4864
	v_pk_fma_f32 v[8:9], v[6:7], v[14:15], v[8:9] op_sel:[0,1,0]
	v_pk_fma_f32 v[10:11], v[6:7], v[18:19], v[10:11] op_sel:[0,1,0]
	ds_read_b128 v[52:55], v80 offset:5120
	v_add_f32_dpp v74, v9, v8 row_ror:8 row_mask:0xf bank_mask:0xf bound_ctrl:1
	v_add_f32_dpp v75, v11, v10 row_ror:8 row_mask:0xf bank_mask:0xf bound_ctrl:1
	ds_read_b128 v[56:59], v80 offset:5632
	v_add_f32_dpp v74, v74, v74 quad_perm:[1,0,3,2] row_mask:0xf bank_mask:0xf bound_ctrl:1
	v_add_f32_dpp v75, v75, v75 quad_perm:[1,0,3,2] row_mask:0xf bank_mask:0xf bound_ctrl:1
	ds_read_b32 v60, v81 offset:5888
	v_add_f32_dpp v74, v74, v74 quad_perm:[2,3,0,1] row_mask:0xf bank_mask:0xf bound_ctrl:1
	v_add_f32_dpp v75, v75, v75 quad_perm:[2,3,0,1] row_mask:0xf bank_mask:0xf bound_ctrl:1
	ds_read_b32 v61, v82 offset:5888
	v_add_f32_dpp v76, v74, v74 row_half_mirror row_mask:0xf bank_mask:0xf bound_ctrl:1
	v_add_f32_dpp v36, v75, v75 row_half_mirror row_mask:0xf bank_mask:0xf bound_ctrl:1
	s_nop 0
	v_mov_b32_dpp v77, v76 row_ror:8 row_mask:0xf bank_mask:0xf bound_ctrl:1
	s_waitcnt lgkmcnt(9)
	v_pk_mul_f32 v[66:67], v[76:77], v[28:29] op_sel_hi:[1,0]
	v_pk_mul_f32 v[68:69], v[76:77], v[28:29] op_sel:[0,1]
	v_pk_mul_f32 v[70:71], v[76:77], v[30:31] op_sel_hi:[1,0]
	v_pk_mul_f32 v[72:73], v[76:77], v[30:31] op_sel:[0,1]
	v_pk_fma_f32 v[66:67], v[32:33], v[24:25], v[66:67] op_sel_hi:[1,0,1]
	v_pk_fma_f32 v[68:69], v[32:33], v[24:25], v[68:69] op_sel:[0,1,0]
	v_pk_fma_f32 v[70:71], v[32:33], v[26:27], v[70:71] op_sel_hi:[1,0,1]
	v_pk_fma_f32 v[72:73], v[32:33], v[26:27], v[72:73] op_sel:[0,1,0]
	v_pk_fma_f32 v[0:1], v[0:1], v[20:21], v[66:67] op_sel_hi:[1,0,1]
	v_pk_fma_f32 v[2:3], v[2:3], v[20:21], v[68:69] op_sel:[0,1,0]
	v_pk_fma_f32 v[4:5], v[4:5], v[22:23], v[70:71] op_sel_hi:[1,0,1]
	v_pk_fma_f32 v[6:7], v[6:7], v[22:23], v[72:73] op_sel:[0,1,0]
	ds_write_b32 v84, v36 offset:256
	ds_write_b32 v84, v76 offset:12544
	s_waitcnt lgkmcnt(7)
	v_pk_mul_f32 v[8:9], v[0:1], v[40:41] op_sel_hi:[1,0]
	v_pk_mul_f32 v[10:11], v[0:1], v[44:45] op_sel_hi:[1,0]
	ds_read_b128 v[12:15], v80 offset:6912
	v_pk_fma_f32 v[8:9], v[2:3], v[40:41], v[8:9] op_sel:[0,1,0]
	v_pk_fma_f32 v[10:11], v[2:3], v[44:45], v[10:11] op_sel:[0,1,0]
	ds_read_b128 v[16:19], v80 offset:6144
	v_pk_fma_f32 v[8:9], v[4:5], v[42:43], v[8:9] op_sel_hi:[1,0,1]
	v_pk_fma_f32 v[10:11], v[4:5], v[46:47], v[10:11] op_sel_hi:[1,0,1]
	ds_read_b128 v[20:23], v80 offset:6400
	v_pk_fma_f32 v[8:9], v[6:7], v[42:43], v[8:9] op_sel:[0,1,0]
	v_pk_fma_f32 v[10:11], v[6:7], v[46:47], v[10:11] op_sel:[0,1,0]
	ds_read_b128 v[24:27], v80 offset:6656
	v_add_f32_dpp v74, v9, v8 row_ror:8 row_mask:0xf bank_mask:0xf bound_ctrl:1
	v_add_f32_dpp v75, v11, v10 row_ror:8 row_mask:0xf bank_mask:0xf bound_ctrl:1
	ds_read_b128 v[28:31], v80 offset:7168
	v_add_f32_dpp v74, v74, v74 quad_perm:[1,0,3,2] row_mask:0xf bank_mask:0xf bound_ctrl:1
	v_add_f32_dpp v75, v75, v75 quad_perm:[1,0,3,2] row_mask:0xf bank_mask:0xf bound_ctrl:1
	ds_read_b32 v32, v81 offset:7424
	v_add_f32_dpp v74, v74, v74 quad_perm:[2,3,0,1] row_mask:0xf bank_mask:0xf bound_ctrl:1
	v_add_f32_dpp v75, v75, v75 quad_perm:[2,3,0,1] row_mask:0xf bank_mask:0xf bound_ctrl:1
	ds_read_b32 v33, v82 offset:7424
	v_add_f32_dpp v76, v74, v74 row_half_mirror row_mask:0xf bank_mask:0xf bound_ctrl:1
	v_add_f32_dpp v64, v75, v75 row_half_mirror row_mask:0xf bank_mask:0xf bound_ctrl:1
	s_nop 0
	v_mov_b32_dpp v77, v76 row_ror:8 row_mask:0xf bank_mask:0xf bound_ctrl:1
	s_waitcnt lgkmcnt(9)
	v_pk_mul_f32 v[66:67], v[76:77], v[56:57] op_sel_hi:[1,0]
	v_pk_mul_f32 v[68:69], v[76:77], v[56:57] op_sel:[0,1]
	v_pk_mul_f32 v[70:71], v[76:77], v[58:59] op_sel_hi:[1,0]
	v_pk_mul_f32 v[72:73], v[76:77], v[58:59] op_sel:[0,1]
	v_pk_fma_f32 v[66:67], v[60:61], v[52:53], v[66:67] op_sel_hi:[1,0,1]
	v_pk_fma_f32 v[68:69], v[60:61], v[52:53], v[68:69] op_sel:[0,1,0]
	v_pk_fma_f32 v[70:71], v[60:61], v[54:55], v[70:71] op_sel_hi:[1,0,1]
	v_pk_fma_f32 v[72:73], v[60:61], v[54:55], v[72:73] op_sel:[0,1,0]
	v_pk_fma_f32 v[0:1], v[0:1], v[48:49], v[66:67] op_sel_hi:[1,0,1]
	v_pk_fma_f32 v[2:3], v[2:3], v[48:49], v[68:69] op_sel:[0,1,0]
	v_pk_fma_f32 v[4:5], v[4:5], v[50:51], v[70:71] op_sel_hi:[1,0,1]
	v_pk_fma_f32 v[6:7], v[6:7], v[50:51], v[72:73] op_sel:[0,1,0]
	ds_write_b32 v84, v64 offset:384
	ds_write_b32 v84, v76 offset:12672
	s_waitcnt lgkmcnt(7)
	v_pk_mul_f32 v[8:9], v[0:1], v[12:13] op_sel_hi:[1,0]
	v_pk_mul_f32 v[10:11], v[0:1], v[16:17] op_sel_hi:[1,0]
	ds_read_b128 v[40:43], v80 offset:8448
	v_pk_fma_f32 v[8:9], v[2:3], v[12:13], v[8:9] op_sel:[0,1,0]
	v_pk_fma_f32 v[10:11], v[2:3], v[16:17], v[10:11] op_sel:[0,1,0]
	ds_read_b128 v[44:47], v80 offset:7680
	v_pk_fma_f32 v[8:9], v[4:5], v[14:15], v[8:9] op_sel_hi:[1,0,1]
	v_pk_fma_f32 v[10:11], v[4:5], v[18:19], v[10:11] op_sel_hi:[1,0,1]
	ds_read_b128 v[48:51], v80 offset:7936
	v_pk_fma_f32 v[8:9], v[6:7], v[14:15], v[8:9] op_sel:[0,1,0]
	v_pk_fma_f32 v[10:11], v[6:7], v[18:19], v[10:11] op_sel:[0,1,0]
	ds_read_b128 v[52:55], v80 offset:8192
	v_add_f32_dpp v74, v9, v8 row_ror:8 row_mask:0xf bank_mask:0xf bound_ctrl:1
	v_add_f32_dpp v75, v11, v10 row_ror:8 row_mask:0xf bank_mask:0xf bound_ctrl:1
	ds_read_b128 v[56:59], v80 offset:8704
	v_add_f32_dpp v74, v74, v74 quad_perm:[1,0,3,2] row_mask:0xf bank_mask:0xf bound_ctrl:1
	v_add_f32_dpp v75, v75, v75 quad_perm:[1,0,3,2] row_mask:0xf bank_mask:0xf bound_ctrl:1
	ds_read_b32 v60, v81 offset:8960
	v_add_f32_dpp v74, v74, v74 quad_perm:[2,3,0,1] row_mask:0xf bank_mask:0xf bound_ctrl:1
	v_add_f32_dpp v75, v75, v75 quad_perm:[2,3,0,1] row_mask:0xf bank_mask:0xf bound_ctrl:1
	ds_read_b32 v61, v82 offset:8960
	v_add_f32_dpp v76, v74, v74 row_half_mirror row_mask:0xf bank_mask:0xf bound_ctrl:1
	v_add_f32_dpp v36, v75, v75 row_half_mirror row_mask:0xf bank_mask:0xf bound_ctrl:1
	s_nop 0
	v_mov_b32_dpp v77, v76 row_ror:8 row_mask:0xf bank_mask:0xf bound_ctrl:1
	s_waitcnt lgkmcnt(9)
	v_pk_mul_f32 v[66:67], v[76:77], v[28:29] op_sel_hi:[1,0]
	v_pk_mul_f32 v[68:69], v[76:77], v[28:29] op_sel:[0,1]
	v_pk_mul_f32 v[70:71], v[76:77], v[30:31] op_sel_hi:[1,0]
	v_pk_mul_f32 v[72:73], v[76:77], v[30:31] op_sel:[0,1]
	v_pk_fma_f32 v[66:67], v[32:33], v[24:25], v[66:67] op_sel_hi:[1,0,1]
	v_pk_fma_f32 v[68:69], v[32:33], v[24:25], v[68:69] op_sel:[0,1,0]
	v_pk_fma_f32 v[70:71], v[32:33], v[26:27], v[70:71] op_sel_hi:[1,0,1]
	v_pk_fma_f32 v[72:73], v[32:33], v[26:27], v[72:73] op_sel:[0,1,0]
	v_pk_fma_f32 v[0:1], v[0:1], v[20:21], v[66:67] op_sel_hi:[1,0,1]
	v_pk_fma_f32 v[2:3], v[2:3], v[20:21], v[68:69] op_sel:[0,1,0]
	v_pk_fma_f32 v[4:5], v[4:5], v[22:23], v[70:71] op_sel_hi:[1,0,1]
	v_pk_fma_f32 v[6:7], v[6:7], v[22:23], v[72:73] op_sel:[0,1,0]
	ds_write_b32 v84, v36 offset:512
	ds_write_b32 v84, v76 offset:12800
	s_waitcnt lgkmcnt(7)
	v_pk_mul_f32 v[8:9], v[0:1], v[40:41] op_sel_hi:[1,0]
	v_pk_mul_f32 v[10:11], v[0:1], v[44:45] op_sel_hi:[1,0]
	ds_read_b128 v[12:15], v80 offset:9984
	v_pk_fma_f32 v[8:9], v[2:3], v[40:41], v[8:9] op_sel:[0,1,0]
	v_pk_fma_f32 v[10:11], v[2:3], v[44:45], v[10:11] op_sel:[0,1,0]
	ds_read_b128 v[16:19], v80 offset:9216
	v_pk_fma_f32 v[8:9], v[4:5], v[42:43], v[8:9] op_sel_hi:[1,0,1]
	v_pk_fma_f32 v[10:11], v[4:5], v[46:47], v[10:11] op_sel_hi:[1,0,1]
	ds_read_b128 v[20:23], v80 offset:9472
	v_pk_fma_f32 v[8:9], v[6:7], v[42:43], v[8:9] op_sel:[0,1,0]
	v_pk_fma_f32 v[10:11], v[6:7], v[46:47], v[10:11] op_sel:[0,1,0]
	ds_read_b128 v[24:27], v80 offset:9728
	v_add_f32_dpp v74, v9, v8 row_ror:8 row_mask:0xf bank_mask:0xf bound_ctrl:1
	v_add_f32_dpp v75, v11, v10 row_ror:8 row_mask:0xf bank_mask:0xf bound_ctrl:1
	ds_read_b128 v[28:31], v80 offset:10240
	v_add_f32_dpp v74, v74, v74 quad_perm:[1,0,3,2] row_mask:0xf bank_mask:0xf bound_ctrl:1
	v_add_f32_dpp v75, v75, v75 quad_perm:[1,0,3,2] row_mask:0xf bank_mask:0xf bound_ctrl:1
	ds_read_b32 v32, v81 offset:10496
	v_add_f32_dpp v74, v74, v74 quad_perm:[2,3,0,1] row_mask:0xf bank_mask:0xf bound_ctrl:1
	v_add_f32_dpp v75, v75, v75 quad_perm:[2,3,0,1] row_mask:0xf bank_mask:0xf bound_ctrl:1
	ds_read_b32 v33, v82 offset:10496
	v_add_f32_dpp v76, v74, v74 row_half_mirror row_mask:0xf bank_mask:0xf bound_ctrl:1
	v_add_f32_dpp v64, v75, v75 row_half_mirror row_mask:0xf bank_mask:0xf bound_ctrl:1
	s_nop 0
	v_mov_b32_dpp v77, v76 row_ror:8 row_mask:0xf bank_mask:0xf bound_ctrl:1
	s_waitcnt lgkmcnt(9)
	v_pk_mul_f32 v[66:67], v[76:77], v[56:57] op_sel_hi:[1,0]
	v_pk_mul_f32 v[68:69], v[76:77], v[56:57] op_sel:[0,1]
	v_pk_mul_f32 v[70:71], v[76:77], v[58:59] op_sel_hi:[1,0]
	v_pk_mul_f32 v[72:73], v[76:77], v[58:59] op_sel:[0,1]
	v_pk_fma_f32 v[66:67], v[60:61], v[52:53], v[66:67] op_sel_hi:[1,0,1]
	v_pk_fma_f32 v[68:69], v[60:61], v[52:53], v[68:69] op_sel:[0,1,0]
	v_pk_fma_f32 v[70:71], v[60:61], v[54:55], v[70:71] op_sel_hi:[1,0,1]
	v_pk_fma_f32 v[72:73], v[60:61], v[54:55], v[72:73] op_sel:[0,1,0]
	v_pk_fma_f32 v[0:1], v[0:1], v[48:49], v[66:67] op_sel_hi:[1,0,1]
	v_pk_fma_f32 v[2:3], v[2:3], v[48:49], v[68:69] op_sel:[0,1,0]
	v_pk_fma_f32 v[4:5], v[4:5], v[50:51], v[70:71] op_sel_hi:[1,0,1]
	v_pk_fma_f32 v[6:7], v[6:7], v[50:51], v[72:73] op_sel:[0,1,0]
	ds_write_b32 v84, v64 offset:640
	ds_write_b32 v84, v76 offset:12928
	s_waitcnt lgkmcnt(7)
	v_pk_mul_f32 v[8:9], v[0:1], v[12:13] op_sel_hi:[1,0]
	v_pk_mul_f32 v[10:11], v[0:1], v[16:17] op_sel_hi:[1,0]
	ds_read_b128 v[40:43], v80 offset:11520
	v_pk_fma_f32 v[8:9], v[2:3], v[12:13], v[8:9] op_sel:[0,1,0]
	v_pk_fma_f32 v[10:11], v[2:3], v[16:17], v[10:11] op_sel:[0,1,0]
	ds_read_b128 v[44:47], v80 offset:10752
	v_pk_fma_f32 v[8:9], v[4:5], v[14:15], v[8:9] op_sel_hi:[1,0,1]
	v_pk_fma_f32 v[10:11], v[4:5], v[18:19], v[10:11] op_sel_hi:[1,0,1]
	ds_read_b128 v[48:51], v80 offset:11008
	v_pk_fma_f32 v[8:9], v[6:7], v[14:15], v[8:9] op_sel:[0,1,0]
	v_pk_fma_f32 v[10:11], v[6:7], v[18:19], v[10:11] op_sel:[0,1,0]
	ds_read_b128 v[52:55], v80 offset:11264
	v_add_f32_dpp v74, v9, v8 row_ror:8 row_mask:0xf bank_mask:0xf bound_ctrl:1
	v_add_f32_dpp v75, v11, v10 row_ror:8 row_mask:0xf bank_mask:0xf bound_ctrl:1
	ds_read_b128 v[56:59], v80 offset:11776
	v_add_f32_dpp v74, v74, v74 quad_perm:[1,0,3,2] row_mask:0xf bank_mask:0xf bound_ctrl:1
	v_add_f32_dpp v75, v75, v75 quad_perm:[1,0,3,2] row_mask:0xf bank_mask:0xf bound_ctrl:1
	ds_read_b32 v60, v81 offset:12032
	v_add_f32_dpp v74, v74, v74 quad_perm:[2,3,0,1] row_mask:0xf bank_mask:0xf bound_ctrl:1
	v_add_f32_dpp v75, v75, v75 quad_perm:[2,3,0,1] row_mask:0xf bank_mask:0xf bound_ctrl:1
	ds_read_b32 v61, v82 offset:12032
	v_add_f32_dpp v76, v74, v74 row_half_mirror row_mask:0xf bank_mask:0xf bound_ctrl:1
	v_add_f32_dpp v36, v75, v75 row_half_mirror row_mask:0xf bank_mask:0xf bound_ctrl:1
	s_nop 0
	v_mov_b32_dpp v77, v76 row_ror:8 row_mask:0xf bank_mask:0xf bound_ctrl:1
	s_waitcnt lgkmcnt(9)
	v_pk_mul_f32 v[66:67], v[76:77], v[28:29] op_sel_hi:[1,0]
	v_pk_mul_f32 v[68:69], v[76:77], v[28:29] op_sel:[0,1]
	v_pk_mul_f32 v[70:71], v[76:77], v[30:31] op_sel_hi:[1,0]
	v_pk_mul_f32 v[72:73], v[76:77], v[30:31] op_sel:[0,1]
	v_pk_fma_f32 v[66:67], v[32:33], v[24:25], v[66:67] op_sel_hi:[1,0,1]
	v_pk_fma_f32 v[68:69], v[32:33], v[24:25], v[68:69] op_sel:[0,1,0]
	v_pk_fma_f32 v[70:71], v[32:33], v[26:27], v[70:71] op_sel_hi:[1,0,1]
	v_pk_fma_f32 v[72:73], v[32:33], v[26:27], v[72:73] op_sel:[0,1,0]
	v_pk_fma_f32 v[0:1], v[0:1], v[20:21], v[66:67] op_sel_hi:[1,0,1]
	v_pk_fma_f32 v[2:3], v[2:3], v[20:21], v[68:69] op_sel:[0,1,0]
	v_pk_fma_f32 v[4:5], v[4:5], v[22:23], v[70:71] op_sel_hi:[1,0,1]
	v_pk_fma_f32 v[6:7], v[6:7], v[22:23], v[72:73] op_sel:[0,1,0]
	ds_write_b32 v84, v36 offset:768
	ds_write_b32 v84, v76 offset:13056
	s_waitcnt lgkmcnt(7)
	v_pk_mul_f32 v[8:9], v[0:1], v[40:41] op_sel_hi:[1,0]
	v_pk_mul_f32 v[10:11], v[0:1], v[44:45] op_sel_hi:[1,0]
	ds_read_b128 v[12:15], v80 offset:13056
	v_pk_fma_f32 v[8:9], v[2:3], v[40:41], v[8:9] op_sel:[0,1,0]
	v_pk_fma_f32 v[10:11], v[2:3], v[44:45], v[10:11] op_sel:[0,1,0]
	ds_read_b128 v[16:19], v80 offset:12288
	v_pk_fma_f32 v[8:9], v[4:5], v[42:43], v[8:9] op_sel_hi:[1,0,1]
	v_pk_fma_f32 v[10:11], v[4:5], v[46:47], v[10:11] op_sel_hi:[1,0,1]
	ds_read_b128 v[20:23], v80 offset:12544
	v_pk_fma_f32 v[8:9], v[6:7], v[42:43], v[8:9] op_sel:[0,1,0]
	v_pk_fma_f32 v[10:11], v[6:7], v[46:47], v[10:11] op_sel:[0,1,0]
	ds_read_b128 v[24:27], v80 offset:12800
	v_add_f32_dpp v74, v9, v8 row_ror:8 row_mask:0xf bank_mask:0xf bound_ctrl:1
	v_add_f32_dpp v75, v11, v10 row_ror:8 row_mask:0xf bank_mask:0xf bound_ctrl:1
	ds_read_b128 v[28:31], v80 offset:13312
	v_add_f32_dpp v74, v74, v74 quad_perm:[1,0,3,2] row_mask:0xf bank_mask:0xf bound_ctrl:1
	v_add_f32_dpp v75, v75, v75 quad_perm:[1,0,3,2] row_mask:0xf bank_mask:0xf bound_ctrl:1
	ds_read_b32 v32, v81 offset:13568
	v_add_f32_dpp v74, v74, v74 quad_perm:[2,3,0,1] row_mask:0xf bank_mask:0xf bound_ctrl:1
	v_add_f32_dpp v75, v75, v75 quad_perm:[2,3,0,1] row_mask:0xf bank_mask:0xf bound_ctrl:1
	ds_read_b32 v33, v82 offset:13568
	v_add_f32_dpp v76, v74, v74 row_half_mirror row_mask:0xf bank_mask:0xf bound_ctrl:1
	v_add_f32_dpp v64, v75, v75 row_half_mirror row_mask:0xf bank_mask:0xf bound_ctrl:1
	s_nop 0
	v_mov_b32_dpp v77, v76 row_ror:8 row_mask:0xf bank_mask:0xf bound_ctrl:1
	s_waitcnt lgkmcnt(9)
	v_pk_mul_f32 v[66:67], v[76:77], v[56:57] op_sel_hi:[1,0]
	v_pk_mul_f32 v[68:69], v[76:77], v[56:57] op_sel:[0,1]
	v_pk_mul_f32 v[70:71], v[76:77], v[58:59] op_sel_hi:[1,0]
	v_pk_mul_f32 v[72:73], v[76:77], v[58:59] op_sel:[0,1]
	v_pk_fma_f32 v[66:67], v[60:61], v[52:53], v[66:67] op_sel_hi:[1,0,1]
	v_pk_fma_f32 v[68:69], v[60:61], v[52:53], v[68:69] op_sel:[0,1,0]
	v_pk_fma_f32 v[70:71], v[60:61], v[54:55], v[70:71] op_sel_hi:[1,0,1]
	v_pk_fma_f32 v[72:73], v[60:61], v[54:55], v[72:73] op_sel:[0,1,0]
	v_pk_fma_f32 v[0:1], v[0:1], v[48:49], v[66:67] op_sel_hi:[1,0,1]
	v_pk_fma_f32 v[2:3], v[2:3], v[48:49], v[68:69] op_sel:[0,1,0]
	v_pk_fma_f32 v[4:5], v[4:5], v[50:51], v[70:71] op_sel_hi:[1,0,1]
	v_pk_fma_f32 v[6:7], v[6:7], v[50:51], v[72:73] op_sel:[0,1,0]
	ds_write_b32 v84, v64 offset:896
	ds_write_b32 v84, v76 offset:13184
	s_waitcnt lgkmcnt(7)
	v_pk_mul_f32 v[8:9], v[0:1], v[12:13] op_sel_hi:[1,0]
	v_pk_mul_f32 v[10:11], v[0:1], v[16:17] op_sel_hi:[1,0]
	ds_read_b128 v[40:43], v80 offset:14592
	v_pk_fma_f32 v[8:9], v[2:3], v[12:13], v[8:9] op_sel:[0,1,0]
	v_pk_fma_f32 v[10:11], v[2:3], v[16:17], v[10:11] op_sel:[0,1,0]
	ds_read_b128 v[44:47], v80 offset:13824
	v_pk_fma_f32 v[8:9], v[4:5], v[14:15], v[8:9] op_sel_hi:[1,0,1]
	v_pk_fma_f32 v[10:11], v[4:5], v[18:19], v[10:11] op_sel_hi:[1,0,1]
	ds_read_b128 v[48:51], v80 offset:14080
	v_pk_fma_f32 v[8:9], v[6:7], v[14:15], v[8:9] op_sel:[0,1,0]
	v_pk_fma_f32 v[10:11], v[6:7], v[18:19], v[10:11] op_sel:[0,1,0]
	ds_read_b128 v[52:55], v80 offset:14336
	v_add_f32_dpp v74, v9, v8 row_ror:8 row_mask:0xf bank_mask:0xf bound_ctrl:1
	v_add_f32_dpp v75, v11, v10 row_ror:8 row_mask:0xf bank_mask:0xf bound_ctrl:1
	ds_read_b128 v[56:59], v80 offset:14848
	v_add_f32_dpp v74, v74, v74 quad_perm:[1,0,3,2] row_mask:0xf bank_mask:0xf bound_ctrl:1
	v_add_f32_dpp v75, v75, v75 quad_perm:[1,0,3,2] row_mask:0xf bank_mask:0xf bound_ctrl:1
	ds_read_b32 v60, v81 offset:15104
	v_add_f32_dpp v74, v74, v74 quad_perm:[2,3,0,1] row_mask:0xf bank_mask:0xf bound_ctrl:1
	v_add_f32_dpp v75, v75, v75 quad_perm:[2,3,0,1] row_mask:0xf bank_mask:0xf bound_ctrl:1
	ds_read_b32 v61, v82 offset:15104
	v_add_f32_dpp v76, v74, v74 row_half_mirror row_mask:0xf bank_mask:0xf bound_ctrl:1
	v_add_f32_dpp v36, v75, v75 row_half_mirror row_mask:0xf bank_mask:0xf bound_ctrl:1
	s_nop 0
	v_mov_b32_dpp v77, v76 row_ror:8 row_mask:0xf bank_mask:0xf bound_ctrl:1
	s_waitcnt lgkmcnt(9)
	v_pk_mul_f32 v[66:67], v[76:77], v[28:29] op_sel_hi:[1,0]
	v_pk_mul_f32 v[68:69], v[76:77], v[28:29] op_sel:[0,1]
	v_pk_mul_f32 v[70:71], v[76:77], v[30:31] op_sel_hi:[1,0]
	v_pk_mul_f32 v[72:73], v[76:77], v[30:31] op_sel:[0,1]
	v_pk_fma_f32 v[66:67], v[32:33], v[24:25], v[66:67] op_sel_hi:[1,0,1]
	v_pk_fma_f32 v[68:69], v[32:33], v[24:25], v[68:69] op_sel:[0,1,0]
	v_pk_fma_f32 v[70:71], v[32:33], v[26:27], v[70:71] op_sel_hi:[1,0,1]
	v_pk_fma_f32 v[72:73], v[32:33], v[26:27], v[72:73] op_sel:[0,1,0]
	v_pk_fma_f32 v[0:1], v[0:1], v[20:21], v[66:67] op_sel_hi:[1,0,1]
	v_pk_fma_f32 v[2:3], v[2:3], v[20:21], v[68:69] op_sel:[0,1,0]
	v_pk_fma_f32 v[4:5], v[4:5], v[22:23], v[70:71] op_sel_hi:[1,0,1]
	v_pk_fma_f32 v[6:7], v[6:7], v[22:23], v[72:73] op_sel:[0,1,0]
	ds_write_b32 v84, v36 offset:1024
	ds_write_b32 v84, v76 offset:13312
	s_waitcnt lgkmcnt(7)
	v_pk_mul_f32 v[8:9], v[0:1], v[40:41] op_sel_hi:[1,0]
	v_pk_mul_f32 v[10:11], v[0:1], v[44:45] op_sel_hi:[1,0]
	ds_read_b128 v[12:15], v80 offset:16128
	v_pk_fma_f32 v[8:9], v[2:3], v[40:41], v[8:9] op_sel:[0,1,0]
	v_pk_fma_f32 v[10:11], v[2:3], v[44:45], v[10:11] op_sel:[0,1,0]
	ds_read_b128 v[16:19], v80 offset:15360
	v_pk_fma_f32 v[8:9], v[4:5], v[42:43], v[8:9] op_sel_hi:[1,0,1]
	v_pk_fma_f32 v[10:11], v[4:5], v[46:47], v[10:11] op_sel_hi:[1,0,1]
	ds_read_b128 v[20:23], v80 offset:15616
	v_pk_fma_f32 v[8:9], v[6:7], v[42:43], v[8:9] op_sel:[0,1,0]
	v_pk_fma_f32 v[10:11], v[6:7], v[46:47], v[10:11] op_sel:[0,1,0]
	ds_read_b128 v[24:27], v80 offset:15872
	v_add_f32_dpp v74, v9, v8 row_ror:8 row_mask:0xf bank_mask:0xf bound_ctrl:1
	v_add_f32_dpp v75, v11, v10 row_ror:8 row_mask:0xf bank_mask:0xf bound_ctrl:1
	ds_read_b128 v[28:31], v80 offset:16384
	v_add_f32_dpp v74, v74, v74 quad_perm:[1,0,3,2] row_mask:0xf bank_mask:0xf bound_ctrl:1
	v_add_f32_dpp v75, v75, v75 quad_perm:[1,0,3,2] row_mask:0xf bank_mask:0xf bound_ctrl:1
	ds_read_b32 v32, v81 offset:16640
	v_add_f32_dpp v74, v74, v74 quad_perm:[2,3,0,1] row_mask:0xf bank_mask:0xf bound_ctrl:1
	v_add_f32_dpp v75, v75, v75 quad_perm:[2,3,0,1] row_mask:0xf bank_mask:0xf bound_ctrl:1
	ds_read_b32 v33, v82 offset:16640
	v_add_f32_dpp v76, v74, v74 row_half_mirror row_mask:0xf bank_mask:0xf bound_ctrl:1
	v_add_f32_dpp v64, v75, v75 row_half_mirror row_mask:0xf bank_mask:0xf bound_ctrl:1
	s_nop 0
	v_mov_b32_dpp v77, v76 row_ror:8 row_mask:0xf bank_mask:0xf bound_ctrl:1
	s_waitcnt lgkmcnt(9)
	v_pk_mul_f32 v[66:67], v[76:77], v[56:57] op_sel_hi:[1,0]
	v_pk_mul_f32 v[68:69], v[76:77], v[56:57] op_sel:[0,1]
	v_pk_mul_f32 v[70:71], v[76:77], v[58:59] op_sel_hi:[1,0]
	v_pk_mul_f32 v[72:73], v[76:77], v[58:59] op_sel:[0,1]
	v_pk_fma_f32 v[66:67], v[60:61], v[52:53], v[66:67] op_sel_hi:[1,0,1]
	v_pk_fma_f32 v[68:69], v[60:61], v[52:53], v[68:69] op_sel:[0,1,0]
	v_pk_fma_f32 v[70:71], v[60:61], v[54:55], v[70:71] op_sel_hi:[1,0,1]
	v_pk_fma_f32 v[72:73], v[60:61], v[54:55], v[72:73] op_sel:[0,1,0]
	v_pk_fma_f32 v[0:1], v[0:1], v[48:49], v[66:67] op_sel_hi:[1,0,1]
	v_pk_fma_f32 v[2:3], v[2:3], v[48:49], v[68:69] op_sel:[0,1,0]
	v_pk_fma_f32 v[4:5], v[4:5], v[50:51], v[70:71] op_sel_hi:[1,0,1]
	v_pk_fma_f32 v[6:7], v[6:7], v[50:51], v[72:73] op_sel:[0,1,0]
	ds_write_b32 v84, v64 offset:1152
	ds_write_b32 v84, v76 offset:13440
	s_waitcnt lgkmcnt(7)
	v_pk_mul_f32 v[8:9], v[0:1], v[12:13] op_sel_hi:[1,0]
	v_pk_mul_f32 v[10:11], v[0:1], v[16:17] op_sel_hi:[1,0]
	ds_read_b128 v[40:43], v80 offset:17664
	v_pk_fma_f32 v[8:9], v[2:3], v[12:13], v[8:9] op_sel:[0,1,0]
	v_pk_fma_f32 v[10:11], v[2:3], v[16:17], v[10:11] op_sel:[0,1,0]
	ds_read_b128 v[44:47], v80 offset:16896
	v_pk_fma_f32 v[8:9], v[4:5], v[14:15], v[8:9] op_sel_hi:[1,0,1]
	v_pk_fma_f32 v[10:11], v[4:5], v[18:19], v[10:11] op_sel_hi:[1,0,1]
	ds_read_b128 v[48:51], v80 offset:17152
	v_pk_fma_f32 v[8:9], v[6:7], v[14:15], v[8:9] op_sel:[0,1,0]
	v_pk_fma_f32 v[10:11], v[6:7], v[18:19], v[10:11] op_sel:[0,1,0]
	ds_read_b128 v[52:55], v80 offset:17408
	v_add_f32_dpp v74, v9, v8 row_ror:8 row_mask:0xf bank_mask:0xf bound_ctrl:1
	v_add_f32_dpp v75, v11, v10 row_ror:8 row_mask:0xf bank_mask:0xf bound_ctrl:1
	ds_read_b128 v[56:59], v80 offset:17920
	v_add_f32_dpp v74, v74, v74 quad_perm:[1,0,3,2] row_mask:0xf bank_mask:0xf bound_ctrl:1
	v_add_f32_dpp v75, v75, v75 quad_perm:[1,0,3,2] row_mask:0xf bank_mask:0xf bound_ctrl:1
	ds_read_b32 v60, v81 offset:18176
	v_add_f32_dpp v74, v74, v74 quad_perm:[2,3,0,1] row_mask:0xf bank_mask:0xf bound_ctrl:1
	v_add_f32_dpp v75, v75, v75 quad_perm:[2,3,0,1] row_mask:0xf bank_mask:0xf bound_ctrl:1
	ds_read_b32 v61, v82 offset:18176
	v_add_f32_dpp v76, v74, v74 row_half_mirror row_mask:0xf bank_mask:0xf bound_ctrl:1
	v_add_f32_dpp v36, v75, v75 row_half_mirror row_mask:0xf bank_mask:0xf bound_ctrl:1
	s_nop 0
	v_mov_b32_dpp v77, v76 row_ror:8 row_mask:0xf bank_mask:0xf bound_ctrl:1
	s_waitcnt lgkmcnt(9)
	v_pk_mul_f32 v[66:67], v[76:77], v[28:29] op_sel_hi:[1,0]
	v_pk_mul_f32 v[68:69], v[76:77], v[28:29] op_sel:[0,1]
	v_pk_mul_f32 v[70:71], v[76:77], v[30:31] op_sel_hi:[1,0]
	v_pk_mul_f32 v[72:73], v[76:77], v[30:31] op_sel:[0,1]
	v_pk_fma_f32 v[66:67], v[32:33], v[24:25], v[66:67] op_sel_hi:[1,0,1]
	v_pk_fma_f32 v[68:69], v[32:33], v[24:25], v[68:69] op_sel:[0,1,0]
	v_pk_fma_f32 v[70:71], v[32:33], v[26:27], v[70:71] op_sel_hi:[1,0,1]
	v_pk_fma_f32 v[72:73], v[32:33], v[26:27], v[72:73] op_sel:[0,1,0]
	v_pk_fma_f32 v[0:1], v[0:1], v[20:21], v[66:67] op_sel_hi:[1,0,1]
	v_pk_fma_f32 v[2:3], v[2:3], v[20:21], v[68:69] op_sel:[0,1,0]
	v_pk_fma_f32 v[4:5], v[4:5], v[22:23], v[70:71] op_sel_hi:[1,0,1]
	v_pk_fma_f32 v[6:7], v[6:7], v[22:23], v[72:73] op_sel:[0,1,0]
	ds_write_b32 v84, v36 offset:1280
	ds_write_b32 v84, v76 offset:13568
	s_waitcnt lgkmcnt(7)
	v_pk_mul_f32 v[8:9], v[0:1], v[40:41] op_sel_hi:[1,0]
	v_pk_mul_f32 v[10:11], v[0:1], v[44:45] op_sel_hi:[1,0]
	ds_read_b128 v[12:15], v80 offset:19200
	v_pk_fma_f32 v[8:9], v[2:3], v[40:41], v[8:9] op_sel:[0,1,0]
	v_pk_fma_f32 v[10:11], v[2:3], v[44:45], v[10:11] op_sel:[0,1,0]
	ds_read_b128 v[16:19], v80 offset:18432
	v_pk_fma_f32 v[8:9], v[4:5], v[42:43], v[8:9] op_sel_hi:[1,0,1]
	v_pk_fma_f32 v[10:11], v[4:5], v[46:47], v[10:11] op_sel_hi:[1,0,1]
	ds_read_b128 v[20:23], v80 offset:18688
	v_pk_fma_f32 v[8:9], v[6:7], v[42:43], v[8:9] op_sel:[0,1,0]
	v_pk_fma_f32 v[10:11], v[6:7], v[46:47], v[10:11] op_sel:[0,1,0]
	ds_read_b128 v[24:27], v80 offset:18944
	v_add_f32_dpp v74, v9, v8 row_ror:8 row_mask:0xf bank_mask:0xf bound_ctrl:1
	v_add_f32_dpp v75, v11, v10 row_ror:8 row_mask:0xf bank_mask:0xf bound_ctrl:1
	ds_read_b128 v[28:31], v80 offset:19456
	v_add_f32_dpp v74, v74, v74 quad_perm:[1,0,3,2] row_mask:0xf bank_mask:0xf bound_ctrl:1
	v_add_f32_dpp v75, v75, v75 quad_perm:[1,0,3,2] row_mask:0xf bank_mask:0xf bound_ctrl:1
	ds_read_b32 v32, v81 offset:19712
	v_add_f32_dpp v74, v74, v74 quad_perm:[2,3,0,1] row_mask:0xf bank_mask:0xf bound_ctrl:1
	v_add_f32_dpp v75, v75, v75 quad_perm:[2,3,0,1] row_mask:0xf bank_mask:0xf bound_ctrl:1
	ds_read_b32 v33, v82 offset:19712
	v_add_f32_dpp v76, v74, v74 row_half_mirror row_mask:0xf bank_mask:0xf bound_ctrl:1
	v_add_f32_dpp v64, v75, v75 row_half_mirror row_mask:0xf bank_mask:0xf bound_ctrl:1
	s_nop 0
	v_mov_b32_dpp v77, v76 row_ror:8 row_mask:0xf bank_mask:0xf bound_ctrl:1
	s_waitcnt lgkmcnt(9)
	v_pk_mul_f32 v[66:67], v[76:77], v[56:57] op_sel_hi:[1,0]
	v_pk_mul_f32 v[68:69], v[76:77], v[56:57] op_sel:[0,1]
	v_pk_mul_f32 v[70:71], v[76:77], v[58:59] op_sel_hi:[1,0]
	v_pk_mul_f32 v[72:73], v[76:77], v[58:59] op_sel:[0,1]
	v_pk_fma_f32 v[66:67], v[60:61], v[52:53], v[66:67] op_sel_hi:[1,0,1]
	v_pk_fma_f32 v[68:69], v[60:61], v[52:53], v[68:69] op_sel:[0,1,0]
	v_pk_fma_f32 v[70:71], v[60:61], v[54:55], v[70:71] op_sel_hi:[1,0,1]
	v_pk_fma_f32 v[72:73], v[60:61], v[54:55], v[72:73] op_sel:[0,1,0]
	v_pk_fma_f32 v[0:1], v[0:1], v[48:49], v[66:67] op_sel_hi:[1,0,1]
	v_pk_fma_f32 v[2:3], v[2:3], v[48:49], v[68:69] op_sel:[0,1,0]
	v_pk_fma_f32 v[4:5], v[4:5], v[50:51], v[70:71] op_sel_hi:[1,0,1]
	v_pk_fma_f32 v[6:7], v[6:7], v[50:51], v[72:73] op_sel:[0,1,0]
	ds_write_b32 v84, v64 offset:1408
	ds_write_b32 v84, v76 offset:13696
	s_waitcnt lgkmcnt(7)
	v_pk_mul_f32 v[8:9], v[0:1], v[12:13] op_sel_hi:[1,0]
	v_pk_mul_f32 v[10:11], v[0:1], v[16:17] op_sel_hi:[1,0]
	ds_read_b128 v[40:43], v80 offset:20736
	v_pk_fma_f32 v[8:9], v[2:3], v[12:13], v[8:9] op_sel:[0,1,0]
	v_pk_fma_f32 v[10:11], v[2:3], v[16:17], v[10:11] op_sel:[0,1,0]
	ds_read_b128 v[44:47], v80 offset:19968
	v_pk_fma_f32 v[8:9], v[4:5], v[14:15], v[8:9] op_sel_hi:[1,0,1]
	v_pk_fma_f32 v[10:11], v[4:5], v[18:19], v[10:11] op_sel_hi:[1,0,1]
	ds_read_b128 v[48:51], v80 offset:20224
	v_pk_fma_f32 v[8:9], v[6:7], v[14:15], v[8:9] op_sel:[0,1,0]
	v_pk_fma_f32 v[10:11], v[6:7], v[18:19], v[10:11] op_sel:[0,1,0]
	ds_read_b128 v[52:55], v80 offset:20480
	v_add_f32_dpp v74, v9, v8 row_ror:8 row_mask:0xf bank_mask:0xf bound_ctrl:1
	v_add_f32_dpp v75, v11, v10 row_ror:8 row_mask:0xf bank_mask:0xf bound_ctrl:1
	ds_read_b128 v[56:59], v80 offset:20992
	v_add_f32_dpp v74, v74, v74 quad_perm:[1,0,3,2] row_mask:0xf bank_mask:0xf bound_ctrl:1
	v_add_f32_dpp v75, v75, v75 quad_perm:[1,0,3,2] row_mask:0xf bank_mask:0xf bound_ctrl:1
	ds_read_b32 v60, v81 offset:21248
	v_add_f32_dpp v74, v74, v74 quad_perm:[2,3,0,1] row_mask:0xf bank_mask:0xf bound_ctrl:1
	v_add_f32_dpp v75, v75, v75 quad_perm:[2,3,0,1] row_mask:0xf bank_mask:0xf bound_ctrl:1
	ds_read_b32 v61, v82 offset:21248
	v_add_f32_dpp v76, v74, v74 row_half_mirror row_mask:0xf bank_mask:0xf bound_ctrl:1
	v_add_f32_dpp v36, v75, v75 row_half_mirror row_mask:0xf bank_mask:0xf bound_ctrl:1
	s_nop 0
	v_mov_b32_dpp v77, v76 row_ror:8 row_mask:0xf bank_mask:0xf bound_ctrl:1
	s_waitcnt lgkmcnt(9)
	v_pk_mul_f32 v[66:67], v[76:77], v[28:29] op_sel_hi:[1,0]
	v_pk_mul_f32 v[68:69], v[76:77], v[28:29] op_sel:[0,1]
	v_pk_mul_f32 v[70:71], v[76:77], v[30:31] op_sel_hi:[1,0]
	v_pk_mul_f32 v[72:73], v[76:77], v[30:31] op_sel:[0,1]
	v_pk_fma_f32 v[66:67], v[32:33], v[24:25], v[66:67] op_sel_hi:[1,0,1]
	v_pk_fma_f32 v[68:69], v[32:33], v[24:25], v[68:69] op_sel:[0,1,0]
	v_pk_fma_f32 v[70:71], v[32:33], v[26:27], v[70:71] op_sel_hi:[1,0,1]
	v_pk_fma_f32 v[72:73], v[32:33], v[26:27], v[72:73] op_sel:[0,1,0]
	v_pk_fma_f32 v[0:1], v[0:1], v[20:21], v[66:67] op_sel_hi:[1,0,1]
	v_pk_fma_f32 v[2:3], v[2:3], v[20:21], v[68:69] op_sel:[0,1,0]
	v_pk_fma_f32 v[4:5], v[4:5], v[22:23], v[70:71] op_sel_hi:[1,0,1]
	v_pk_fma_f32 v[6:7], v[6:7], v[22:23], v[72:73] op_sel:[0,1,0]
	ds_write_b32 v84, v36 offset:1536
	ds_write_b32 v84, v76 offset:13824
	s_waitcnt lgkmcnt(7)
	v_pk_mul_f32 v[8:9], v[0:1], v[40:41] op_sel_hi:[1,0]
	v_pk_mul_f32 v[10:11], v[0:1], v[44:45] op_sel_hi:[1,0]
	ds_read_b128 v[12:15], v80 offset:22272
	v_pk_fma_f32 v[8:9], v[2:3], v[40:41], v[8:9] op_sel:[0,1,0]
	v_pk_fma_f32 v[10:11], v[2:3], v[44:45], v[10:11] op_sel:[0,1,0]
	ds_read_b128 v[16:19], v80 offset:21504
	v_pk_fma_f32 v[8:9], v[4:5], v[42:43], v[8:9] op_sel_hi:[1,0,1]
	v_pk_fma_f32 v[10:11], v[4:5], v[46:47], v[10:11] op_sel_hi:[1,0,1]
	ds_read_b128 v[20:23], v80 offset:21760
	v_pk_fma_f32 v[8:9], v[6:7], v[42:43], v[8:9] op_sel:[0,1,0]
	v_pk_fma_f32 v[10:11], v[6:7], v[46:47], v[10:11] op_sel:[0,1,0]
	ds_read_b128 v[24:27], v80 offset:22016
	v_add_f32_dpp v74, v9, v8 row_ror:8 row_mask:0xf bank_mask:0xf bound_ctrl:1
	v_add_f32_dpp v75, v11, v10 row_ror:8 row_mask:0xf bank_mask:0xf bound_ctrl:1
	ds_read_b128 v[28:31], v80 offset:22528
	v_add_f32_dpp v74, v74, v74 quad_perm:[1,0,3,2] row_mask:0xf bank_mask:0xf bound_ctrl:1
	v_add_f32_dpp v75, v75, v75 quad_perm:[1,0,3,2] row_mask:0xf bank_mask:0xf bound_ctrl:1
	ds_read_b32 v32, v81 offset:22784
	v_add_f32_dpp v74, v74, v74 quad_perm:[2,3,0,1] row_mask:0xf bank_mask:0xf bound_ctrl:1
	v_add_f32_dpp v75, v75, v75 quad_perm:[2,3,0,1] row_mask:0xf bank_mask:0xf bound_ctrl:1
	ds_read_b32 v33, v82 offset:22784
	v_add_f32_dpp v76, v74, v74 row_half_mirror row_mask:0xf bank_mask:0xf bound_ctrl:1
	v_add_f32_dpp v64, v75, v75 row_half_mirror row_mask:0xf bank_mask:0xf bound_ctrl:1
	s_nop 0
	v_mov_b32_dpp v77, v76 row_ror:8 row_mask:0xf bank_mask:0xf bound_ctrl:1
	s_waitcnt lgkmcnt(9)
	v_pk_mul_f32 v[66:67], v[76:77], v[56:57] op_sel_hi:[1,0]
	v_pk_mul_f32 v[68:69], v[76:77], v[56:57] op_sel:[0,1]
	v_pk_mul_f32 v[70:71], v[76:77], v[58:59] op_sel_hi:[1,0]
	v_pk_mul_f32 v[72:73], v[76:77], v[58:59] op_sel:[0,1]
	v_pk_fma_f32 v[66:67], v[60:61], v[52:53], v[66:67] op_sel_hi:[1,0,1]
	v_pk_fma_f32 v[68:69], v[60:61], v[52:53], v[68:69] op_sel:[0,1,0]
	v_pk_fma_f32 v[70:71], v[60:61], v[54:55], v[70:71] op_sel_hi:[1,0,1]
	v_pk_fma_f32 v[72:73], v[60:61], v[54:55], v[72:73] op_sel:[0,1,0]
	v_pk_fma_f32 v[0:1], v[0:1], v[48:49], v[66:67] op_sel_hi:[1,0,1]
	v_pk_fma_f32 v[2:3], v[2:3], v[48:49], v[68:69] op_sel:[0,1,0]
	v_pk_fma_f32 v[4:5], v[4:5], v[50:51], v[70:71] op_sel_hi:[1,0,1]
	v_pk_fma_f32 v[6:7], v[6:7], v[50:51], v[72:73] op_sel:[0,1,0]
	ds_write_b32 v84, v64 offset:1664
	ds_write_b32 v84, v76 offset:13952
	s_waitcnt lgkmcnt(7)
	v_pk_mul_f32 v[8:9], v[0:1], v[12:13] op_sel_hi:[1,0]
	v_pk_mul_f32 v[10:11], v[0:1], v[16:17] op_sel_hi:[1,0]
	ds_read_b128 v[40:43], v80 offset:23808
	v_pk_fma_f32 v[8:9], v[2:3], v[12:13], v[8:9] op_sel:[0,1,0]
	v_pk_fma_f32 v[10:11], v[2:3], v[16:17], v[10:11] op_sel:[0,1,0]
	ds_read_b128 v[44:47], v80 offset:23040
	v_pk_fma_f32 v[8:9], v[4:5], v[14:15], v[8:9] op_sel_hi:[1,0,1]
	v_pk_fma_f32 v[10:11], v[4:5], v[18:19], v[10:11] op_sel_hi:[1,0,1]
	ds_read_b128 v[48:51], v80 offset:23296
	v_pk_fma_f32 v[8:9], v[6:7], v[14:15], v[8:9] op_sel:[0,1,0]
	v_pk_fma_f32 v[10:11], v[6:7], v[18:19], v[10:11] op_sel:[0,1,0]
	ds_read_b128 v[52:55], v80 offset:23552
	v_add_f32_dpp v74, v9, v8 row_ror:8 row_mask:0xf bank_mask:0xf bound_ctrl:1
	v_add_f32_dpp v75, v11, v10 row_ror:8 row_mask:0xf bank_mask:0xf bound_ctrl:1
	ds_read_b128 v[56:59], v80 offset:24064
	v_add_f32_dpp v74, v74, v74 quad_perm:[1,0,3,2] row_mask:0xf bank_mask:0xf bound_ctrl:1
	v_add_f32_dpp v75, v75, v75 quad_perm:[1,0,3,2] row_mask:0xf bank_mask:0xf bound_ctrl:1
	ds_read_b32 v60, v81 offset:24320
	v_add_f32_dpp v74, v74, v74 quad_perm:[2,3,0,1] row_mask:0xf bank_mask:0xf bound_ctrl:1
	v_add_f32_dpp v75, v75, v75 quad_perm:[2,3,0,1] row_mask:0xf bank_mask:0xf bound_ctrl:1
	ds_read_b32 v61, v82 offset:24320
	v_add_f32_dpp v76, v74, v74 row_half_mirror row_mask:0xf bank_mask:0xf bound_ctrl:1
	v_add_f32_dpp v36, v75, v75 row_half_mirror row_mask:0xf bank_mask:0xf bound_ctrl:1
	s_nop 0
	v_mov_b32_dpp v77, v76 row_ror:8 row_mask:0xf bank_mask:0xf bound_ctrl:1
	s_waitcnt lgkmcnt(9)
	v_pk_mul_f32 v[66:67], v[76:77], v[28:29] op_sel_hi:[1,0]
	v_pk_mul_f32 v[68:69], v[76:77], v[28:29] op_sel:[0,1]
	v_pk_mul_f32 v[70:71], v[76:77], v[30:31] op_sel_hi:[1,0]
	v_pk_mul_f32 v[72:73], v[76:77], v[30:31] op_sel:[0,1]
	v_pk_fma_f32 v[66:67], v[32:33], v[24:25], v[66:67] op_sel_hi:[1,0,1]
	v_pk_fma_f32 v[68:69], v[32:33], v[24:25], v[68:69] op_sel:[0,1,0]
	v_pk_fma_f32 v[70:71], v[32:33], v[26:27], v[70:71] op_sel_hi:[1,0,1]
	v_pk_fma_f32 v[72:73], v[32:33], v[26:27], v[72:73] op_sel:[0,1,0]
	v_pk_fma_f32 v[0:1], v[0:1], v[20:21], v[66:67] op_sel_hi:[1,0,1]
	v_pk_fma_f32 v[2:3], v[2:3], v[20:21], v[68:69] op_sel:[0,1,0]
	v_pk_fma_f32 v[4:5], v[4:5], v[22:23], v[70:71] op_sel_hi:[1,0,1]
	v_pk_fma_f32 v[6:7], v[6:7], v[22:23], v[72:73] op_sel:[0,1,0]
	ds_write_b32 v84, v36 offset:1792
	ds_write_b32 v84, v76 offset:14080
	s_waitcnt lgkmcnt(7)
	v_pk_mul_f32 v[8:9], v[0:1], v[40:41] op_sel_hi:[1,0]
	v_pk_mul_f32 v[10:11], v[0:1], v[44:45] op_sel_hi:[1,0]
	ds_read_b128 v[12:15], v80 offset:25344
	v_pk_fma_f32 v[8:9], v[2:3], v[40:41], v[8:9] op_sel:[0,1,0]
	v_pk_fma_f32 v[10:11], v[2:3], v[44:45], v[10:11] op_sel:[0,1,0]
	ds_read_b128 v[16:19], v80 offset:24576
	v_pk_fma_f32 v[8:9], v[4:5], v[42:43], v[8:9] op_sel_hi:[1,0,1]
	v_pk_fma_f32 v[10:11], v[4:5], v[46:47], v[10:11] op_sel_hi:[1,0,1]
	ds_read_b128 v[20:23], v80 offset:24832
	v_pk_fma_f32 v[8:9], v[6:7], v[42:43], v[8:9] op_sel:[0,1,0]
	v_pk_fma_f32 v[10:11], v[6:7], v[46:47], v[10:11] op_sel:[0,1,0]
	ds_read_b128 v[24:27], v80 offset:25088
	v_add_f32_dpp v74, v9, v8 row_ror:8 row_mask:0xf bank_mask:0xf bound_ctrl:1
	v_add_f32_dpp v75, v11, v10 row_ror:8 row_mask:0xf bank_mask:0xf bound_ctrl:1
	ds_read_b128 v[28:31], v80 offset:25600
	v_add_f32_dpp v74, v74, v74 quad_perm:[1,0,3,2] row_mask:0xf bank_mask:0xf bound_ctrl:1
	v_add_f32_dpp v75, v75, v75 quad_perm:[1,0,3,2] row_mask:0xf bank_mask:0xf bound_ctrl:1
	ds_read_b32 v32, v81 offset:25856
	v_add_f32_dpp v74, v74, v74 quad_perm:[2,3,0,1] row_mask:0xf bank_mask:0xf bound_ctrl:1
	v_add_f32_dpp v75, v75, v75 quad_perm:[2,3,0,1] row_mask:0xf bank_mask:0xf bound_ctrl:1
	ds_read_b32 v33, v82 offset:25856
	v_add_f32_dpp v76, v74, v74 row_half_mirror row_mask:0xf bank_mask:0xf bound_ctrl:1
	v_add_f32_dpp v64, v75, v75 row_half_mirror row_mask:0xf bank_mask:0xf bound_ctrl:1
	s_nop 0
	v_mov_b32_dpp v77, v76 row_ror:8 row_mask:0xf bank_mask:0xf bound_ctrl:1
	s_waitcnt lgkmcnt(9)
	v_pk_mul_f32 v[66:67], v[76:77], v[56:57] op_sel_hi:[1,0]
	v_pk_mul_f32 v[68:69], v[76:77], v[56:57] op_sel:[0,1]
	v_pk_mul_f32 v[70:71], v[76:77], v[58:59] op_sel_hi:[1,0]
	v_pk_mul_f32 v[72:73], v[76:77], v[58:59] op_sel:[0,1]
	v_pk_fma_f32 v[66:67], v[60:61], v[52:53], v[66:67] op_sel_hi:[1,0,1]
	v_pk_fma_f32 v[68:69], v[60:61], v[52:53], v[68:69] op_sel:[0,1,0]
	v_pk_fma_f32 v[70:71], v[60:61], v[54:55], v[70:71] op_sel_hi:[1,0,1]
	v_pk_fma_f32 v[72:73], v[60:61], v[54:55], v[72:73] op_sel:[0,1,0]
	v_pk_fma_f32 v[0:1], v[0:1], v[48:49], v[66:67] op_sel_hi:[1,0,1]
	v_pk_fma_f32 v[2:3], v[2:3], v[48:49], v[68:69] op_sel:[0,1,0]
	v_pk_fma_f32 v[4:5], v[4:5], v[50:51], v[70:71] op_sel_hi:[1,0,1]
	v_pk_fma_f32 v[6:7], v[6:7], v[50:51], v[72:73] op_sel:[0,1,0]
	ds_write_b32 v84, v64 offset:1920
	ds_write_b32 v84, v76 offset:14208
	s_cmp_eq_u32 s4, 64
	s_cbranch_scc1 .Lrec_chunk_end
	s_waitcnt lgkmcnt(7)
	v_pk_mul_f32 v[8:9], v[0:1], v[12:13] op_sel_hi:[1,0]
	v_pk_mul_f32 v[10:11], v[0:1], v[16:17] op_sel_hi:[1,0]
	ds_read_b128 v[40:43], v80 offset:26880
	v_pk_fma_f32 v[8:9], v[2:3], v[12:13], v[8:9] op_sel:[0,1,0]
	v_pk_fma_f32 v[10:11], v[2:3], v[16:17], v[10:11] op_sel:[0,1,0]
	ds_read_b128 v[44:47], v80 offset:26112
	v_pk_fma_f32 v[8:9], v[4:5], v[14:15], v[8:9] op_sel_hi:[1,0,1]
	v_pk_fma_f32 v[10:11], v[4:5], v[18:19], v[10:11] op_sel_hi:[1,0,1]
	ds_read_b128 v[48:51], v80 offset:26368
	v_pk_fma_f32 v[8:9], v[6:7], v[14:15], v[8:9] op_sel:[0,1,0]
	v_pk_fma_f32 v[10:11], v[6:7], v[18:19], v[10:11] op_sel:[0,1,0]
	ds_read_b128 v[52:55], v80 offset:26624
	v_add_f32_dpp v74, v9, v8 row_ror:8 row_mask:0xf bank_mask:0xf bound_ctrl:1
	v_add_f32_dpp v75, v11, v10 row_ror:8 row_mask:0xf bank_mask:0xf bound_ctrl:1
	ds_read_b128 v[56:59], v80 offset:27136
	v_add_f32_dpp v74, v74, v74 quad_perm:[1,0,3,2] row_mask:0xf bank_mask:0xf bound_ctrl:1
	v_add_f32_dpp v75, v75, v75 quad_perm:[1,0,3,2] row_mask:0xf bank_mask:0xf bound_ctrl:1
	ds_read_b32 v60, v81 offset:27392
	v_add_f32_dpp v74, v74, v74 quad_perm:[2,3,0,1] row_mask:0xf bank_mask:0xf bound_ctrl:1
	v_add_f32_dpp v75, v75, v75 quad_perm:[2,3,0,1] row_mask:0xf bank_mask:0xf bound_ctrl:1
	ds_read_b32 v61, v82 offset:27392
	v_add_f32_dpp v76, v74, v74 row_half_mirror row_mask:0xf bank_mask:0xf bound_ctrl:1
	v_add_f32_dpp v36, v75, v75 row_half_mirror row_mask:0xf bank_mask:0xf bound_ctrl:1
	s_nop 0
	v_mov_b32_dpp v77, v76 row_ror:8 row_mask:0xf bank_mask:0xf bound_ctrl:1
	s_waitcnt lgkmcnt(9)
	v_pk_mul_f32 v[66:67], v[76:77], v[28:29] op_sel_hi:[1,0]
	v_pk_mul_f32 v[68:69], v[76:77], v[28:29] op_sel:[0,1]
	v_pk_mul_f32 v[70:71], v[76:77], v[30:31] op_sel_hi:[1,0]
	v_pk_mul_f32 v[72:73], v[76:77], v[30:31] op_sel:[0,1]
	v_pk_fma_f32 v[66:67], v[32:33], v[24:25], v[66:67] op_sel_hi:[1,0,1]
	v_pk_fma_f32 v[68:69], v[32:33], v[24:25], v[68:69] op_sel:[0,1,0]
	v_pk_fma_f32 v[70:71], v[32:33], v[26:27], v[70:71] op_sel_hi:[1,0,1]
	v_pk_fma_f32 v[72:73], v[32:33], v[26:27], v[72:73] op_sel:[0,1,0]
	v_pk_fma_f32 v[0:1], v[0:1], v[20:21], v[66:67] op_sel_hi:[1,0,1]
	v_pk_fma_f32 v[2:3], v[2:3], v[20:21], v[68:69] op_sel:[0,1,0]
	v_pk_fma_f32 v[4:5], v[4:5], v[22:23], v[70:71] op_sel_hi:[1,0,1]
	v_pk_fma_f32 v[6:7], v[6:7], v[22:23], v[72:73] op_sel:[0,1,0]
	ds_write_b32 v84, v36 offset:2048
	ds_write_b32 v84, v76 offset:14336
	s_waitcnt lgkmcnt(7)
	v_pk_mul_f32 v[8:9], v[0:1], v[40:41] op_sel_hi:[1,0]
	v_pk_mul_f32 v[10:11], v[0:1], v[44:45] op_sel_hi:[1,0]
	ds_read_b128 v[12:15], v80 offset:28416
	v_pk_fma_f32 v[8:9], v[2:3], v[40:41], v[8:9] op_sel:[0,1,0]
	v_pk_fma_f32 v[10:11], v[2:3], v[44:45], v[10:11] op_sel:[0,1,0]
	ds_read_b128 v[16:19], v80 offset:27648
	v_pk_fma_f32 v[8:9], v[4:5], v[42:43], v[8:9] op_sel_hi:[1,0,1]
	v_pk_fma_f32 v[10:11], v[4:5], v[46:47], v[10:11] op_sel_hi:[1,0,1]
	ds_read_b128 v[20:23], v80 offset:27904
	v_pk_fma_f32 v[8:9], v[6:7], v[42:43], v[8:9] op_sel:[0,1,0]
	v_pk_fma_f32 v[10:11], v[6:7], v[46:47], v[10:11] op_sel:[0,1,0]
	ds_read_b128 v[24:27], v80 offset:28160
	v_add_f32_dpp v74, v9, v8 row_ror:8 row_mask:0xf bank_mask:0xf bound_ctrl:1
	v_add_f32_dpp v75, v11, v10 row_ror:8 row_mask:0xf bank_mask:0xf bound_ctrl:1
	ds_read_b128 v[28:31], v80 offset:28672
	v_add_f32_dpp v74, v74, v74 quad_perm:[1,0,3,2] row_mask:0xf bank_mask:0xf bound_ctrl:1
	v_add_f32_dpp v75, v75, v75 quad_perm:[1,0,3,2] row_mask:0xf bank_mask:0xf bound_ctrl:1
	ds_read_b32 v32, v81 offset:28928
	v_add_f32_dpp v74, v74, v74 quad_perm:[2,3,0,1] row_mask:0xf bank_mask:0xf bound_ctrl:1
	v_add_f32_dpp v75, v75, v75 quad_perm:[2,3,0,1] row_mask:0xf bank_mask:0xf bound_ctrl:1
	ds_read_b32 v33, v82 offset:28928
	v_add_f32_dpp v76, v74, v74 row_half_mirror row_mask:0xf bank_mask:0xf bound_ctrl:1
	v_add_f32_dpp v64, v75, v75 row_half_mirror row_mask:0xf bank_mask:0xf bound_ctrl:1
	s_nop 0
	v_mov_b32_dpp v77, v76 row_ror:8 row_mask:0xf bank_mask:0xf bound_ctrl:1
	s_waitcnt lgkmcnt(9)
	v_pk_mul_f32 v[66:67], v[76:77], v[56:57] op_sel_hi:[1,0]
	v_pk_mul_f32 v[68:69], v[76:77], v[56:57] op_sel:[0,1]
	v_pk_mul_f32 v[70:71], v[76:77], v[58:59] op_sel_hi:[1,0]
	v_pk_mul_f32 v[72:73], v[76:77], v[58:59] op_sel:[0,1]
	v_pk_fma_f32 v[66:67], v[60:61], v[52:53], v[66:67] op_sel_hi:[1,0,1]
	v_pk_fma_f32 v[68:69], v[60:61], v[52:53], v[68:69] op_sel:[0,1,0]
	v_pk_fma_f32 v[70:71], v[60:61], v[54:55], v[70:71] op_sel_hi:[1,0,1]
	v_pk_fma_f32 v[72:73], v[60:61], v[54:55], v[72:73] op_sel:[0,1,0]
	v_pk_fma_f32 v[0:1], v[0:1], v[48:49], v[66:67] op_sel_hi:[1,0,1]
	v_pk_fma_f32 v[2:3], v[2:3], v[48:49], v[68:69] op_sel:[0,1,0]
	v_pk_fma_f32 v[4:5], v[4:5], v[50:51], v[70:71] op_sel_hi:[1,0,1]
	v_pk_fma_f32 v[6:7], v[6:7], v[50:51], v[72:73] op_sel:[0,1,0]
	ds_write_b32 v84, v64 offset:2176
	ds_write_b32 v84, v76 offset:14464
	s_waitcnt lgkmcnt(7)
	v_pk_mul_f32 v[8:9], v[0:1], v[12:13] op_sel_hi:[1,0]
	v_pk_mul_f32 v[10:11], v[0:1], v[16:17] op_sel_hi:[1,0]
	ds_read_b128 v[40:43], v80 offset:29952
	v_pk_fma_f32 v[8:9], v[2:3], v[12:13], v[8:9] op_sel:[0,1,0]
	v_pk_fma_f32 v[10:11], v[2:3], v[16:17], v[10:11] op_sel:[0,1,0]
	ds_read_b128 v[44:47], v80 offset:29184
	v_pk_fma_f32 v[8:9], v[4:5], v[14:15], v[8:9] op_sel_hi:[1,0,1]
	v_pk_fma_f32 v[10:11], v[4:5], v[18:19], v[10:11] op_sel_hi:[1,0,1]
	ds_read_b128 v[48:51], v80 offset:29440
	v_pk_fma_f32 v[8:9], v[6:7], v[14:15], v[8:9] op_sel:[0,1,0]
	v_pk_fma_f32 v[10:11], v[6:7], v[18:19], v[10:11] op_sel:[0,1,0]
	ds_read_b128 v[52:55], v80 offset:29696
	v_add_f32_dpp v74, v9, v8 row_ror:8 row_mask:0xf bank_mask:0xf bound_ctrl:1
	v_add_f32_dpp v75, v11, v10 row_ror:8 row_mask:0xf bank_mask:0xf bound_ctrl:1
	ds_read_b128 v[56:59], v80 offset:30208
	v_add_f32_dpp v74, v74, v74 quad_perm:[1,0,3,2] row_mask:0xf bank_mask:0xf bound_ctrl:1
	v_add_f32_dpp v75, v75, v75 quad_perm:[1,0,3,2] row_mask:0xf bank_mask:0xf bound_ctrl:1
	ds_read_b32 v60, v81 offset:30464
	v_add_f32_dpp v74, v74, v74 quad_perm:[2,3,0,1] row_mask:0xf bank_mask:0xf bound_ctrl:1
	v_add_f32_dpp v75, v75, v75 quad_perm:[2,3,0,1] row_mask:0xf bank_mask:0xf bound_ctrl:1
	ds_read_b32 v61, v82 offset:30464
	v_add_f32_dpp v76, v74, v74 row_half_mirror row_mask:0xf bank_mask:0xf bound_ctrl:1
	v_add_f32_dpp v36, v75, v75 row_half_mirror row_mask:0xf bank_mask:0xf bound_ctrl:1
	s_nop 0
	v_mov_b32_dpp v77, v76 row_ror:8 row_mask:0xf bank_mask:0xf bound_ctrl:1
	s_waitcnt lgkmcnt(9)
	v_pk_mul_f32 v[66:67], v[76:77], v[28:29] op_sel_hi:[1,0]
	v_pk_mul_f32 v[68:69], v[76:77], v[28:29] op_sel:[0,1]
	v_pk_mul_f32 v[70:71], v[76:77], v[30:31] op_sel_hi:[1,0]
	v_pk_mul_f32 v[72:73], v[76:77], v[30:31] op_sel:[0,1]
	v_pk_fma_f32 v[66:67], v[32:33], v[24:25], v[66:67] op_sel_hi:[1,0,1]
	v_pk_fma_f32 v[68:69], v[32:33], v[24:25], v[68:69] op_sel:[0,1,0]
	v_pk_fma_f32 v[70:71], v[32:33], v[26:27], v[70:71] op_sel_hi:[1,0,1]
	v_pk_fma_f32 v[72:73], v[32:33], v[26:27], v[72:73] op_sel:[0,1,0]
	v_pk_fma_f32 v[0:1], v[0:1], v[20:21], v[66:67] op_sel_hi:[1,0,1]
	v_pk_fma_f32 v[2:3], v[2:3], v[20:21], v[68:69] op_sel:[0,1,0]
	v_pk_fma_f32 v[4:5], v[4:5], v[22:23], v[70:71] op_sel_hi:[1,0,1]
	v_pk_fma_f32 v[6:7], v[6:7], v[22:23], v[72:73] op_sel:[0,1,0]
	ds_write_b32 v84, v36 offset:2304
	ds_write_b32 v84, v76 offset:14592
	s_waitcnt lgkmcnt(7)
	v_pk_mul_f32 v[8:9], v[0:1], v[40:41] op_sel_hi:[1,0]
	v_pk_mul_f32 v[10:11], v[0:1], v[44:45] op_sel_hi:[1,0]
	ds_read_b128 v[12:15], v80 offset:31488
	v_pk_fma_f32 v[8:9], v[2:3], v[40:41], v[8:9] op_sel:[0,1,0]
	v_pk_fma_f32 v[10:11], v[2:3], v[44:45], v[10:11] op_sel:[0,1,0]
	ds_read_b128 v[16:19], v80 offset:30720
	v_pk_fma_f32 v[8:9], v[4:5], v[42:43], v[8:9] op_sel_hi:[1,0,1]
	v_pk_fma_f32 v[10:11], v[4:5], v[46:47], v[10:11] op_sel_hi:[1,0,1]
	ds_read_b128 v[20:23], v80 offset:30976
	v_pk_fma_f32 v[8:9], v[6:7], v[42:43], v[8:9] op_sel:[0,1,0]
	v_pk_fma_f32 v[10:11], v[6:7], v[46:47], v[10:11] op_sel:[0,1,0]
	ds_read_b128 v[24:27], v80 offset:31232
	v_add_f32_dpp v74, v9, v8 row_ror:8 row_mask:0xf bank_mask:0xf bound_ctrl:1
	v_add_f32_dpp v75, v11, v10 row_ror:8 row_mask:0xf bank_mask:0xf bound_ctrl:1
	ds_read_b128 v[28:31], v80 offset:31744
	v_add_f32_dpp v74, v74, v74 quad_perm:[1,0,3,2] row_mask:0xf bank_mask:0xf bound_ctrl:1
	v_add_f32_dpp v75, v75, v75 quad_perm:[1,0,3,2] row_mask:0xf bank_mask:0xf bound_ctrl:1
	ds_read_b32 v32, v81 offset:32000
	v_add_f32_dpp v74, v74, v74 quad_perm:[2,3,0,1] row_mask:0xf bank_mask:0xf bound_ctrl:1
	v_add_f32_dpp v75, v75, v75 quad_perm:[2,3,0,1] row_mask:0xf bank_mask:0xf bound_ctrl:1
	ds_read_b32 v33, v82 offset:32000
	v_add_f32_dpp v76, v74, v74 row_half_mirror row_mask:0xf bank_mask:0xf bound_ctrl:1
	v_add_f32_dpp v64, v75, v75 row_half_mirror row_mask:0xf bank_mask:0xf bound_ctrl:1
	s_nop 0
	v_mov_b32_dpp v77, v76 row_ror:8 row_mask:0xf bank_mask:0xf bound_ctrl:1
	s_waitcnt lgkmcnt(9)
	v_pk_mul_f32 v[66:67], v[76:77], v[56:57] op_sel_hi:[1,0]
	v_pk_mul_f32 v[68:69], v[76:77], v[56:57] op_sel:[0,1]
	v_pk_mul_f32 v[70:71], v[76:77], v[58:59] op_sel_hi:[1,0]
	v_pk_mul_f32 v[72:73], v[76:77], v[58:59] op_sel:[0,1]
	v_pk_fma_f32 v[66:67], v[60:61], v[52:53], v[66:67] op_sel_hi:[1,0,1]
	v_pk_fma_f32 v[68:69], v[60:61], v[52:53], v[68:69] op_sel:[0,1,0]
	v_pk_fma_f32 v[70:71], v[60:61], v[54:55], v[70:71] op_sel_hi:[1,0,1]
	v_pk_fma_f32 v[72:73], v[60:61], v[54:55], v[72:73] op_sel:[0,1,0]
	v_pk_fma_f32 v[0:1], v[0:1], v[48:49], v[66:67] op_sel_hi:[1,0,1]
	v_pk_fma_f32 v[2:3], v[2:3], v[48:49], v[68:69] op_sel:[0,1,0]
	v_pk_fma_f32 v[4:5], v[4:5], v[50:51], v[70:71] op_sel_hi:[1,0,1]
	v_pk_fma_f32 v[6:7], v[6:7], v[50:51], v[72:73] op_sel:[0,1,0]
	ds_write_b32 v84, v64 offset:2432
	ds_write_b32 v84, v76 offset:14720
	s_waitcnt lgkmcnt(7)
	v_pk_mul_f32 v[8:9], v[0:1], v[12:13] op_sel_hi:[1,0]
	v_pk_mul_f32 v[10:11], v[0:1], v[16:17] op_sel_hi:[1,0]
	ds_read_b128 v[40:43], v80 offset:33024
	v_pk_fma_f32 v[8:9], v[2:3], v[12:13], v[8:9] op_sel:[0,1,0]
	v_pk_fma_f32 v[10:11], v[2:3], v[16:17], v[10:11] op_sel:[0,1,0]
	ds_read_b128 v[44:47], v80 offset:32256
	v_pk_fma_f32 v[8:9], v[4:5], v[14:15], v[8:9] op_sel_hi:[1,0,1]
	v_pk_fma_f32 v[10:11], v[4:5], v[18:19], v[10:11] op_sel_hi:[1,0,1]
	ds_read_b128 v[48:51], v80 offset:32512
	v_pk_fma_f32 v[8:9], v[6:7], v[14:15], v[8:9] op_sel:[0,1,0]
	v_pk_fma_f32 v[10:11], v[6:7], v[18:19], v[10:11] op_sel:[0,1,0]
	ds_read_b128 v[52:55], v80 offset:32768
	v_add_f32_dpp v74, v9, v8 row_ror:8 row_mask:0xf bank_mask:0xf bound_ctrl:1
	v_add_f32_dpp v75, v11, v10 row_ror:8 row_mask:0xf bank_mask:0xf bound_ctrl:1
	ds_read_b128 v[56:59], v80 offset:33280
	v_add_f32_dpp v74, v74, v74 quad_perm:[1,0,3,2] row_mask:0xf bank_mask:0xf bound_ctrl:1
	v_add_f32_dpp v75, v75, v75 quad_perm:[1,0,3,2] row_mask:0xf bank_mask:0xf bound_ctrl:1
	ds_read_b32 v60, v81 offset:33536
	v_add_f32_dpp v74, v74, v74 quad_perm:[2,3,0,1] row_mask:0xf bank_mask:0xf bound_ctrl:1
	v_add_f32_dpp v75, v75, v75 quad_perm:[2,3,0,1] row_mask:0xf bank_mask:0xf bound_ctrl:1
	ds_read_b32 v61, v82 offset:33536
	v_add_f32_dpp v76, v74, v74 row_half_mirror row_mask:0xf bank_mask:0xf bound_ctrl:1
	v_add_f32_dpp v36, v75, v75 row_half_mirror row_mask:0xf bank_mask:0xf bound_ctrl:1
	s_nop 0
	v_mov_b32_dpp v77, v76 row_ror:8 row_mask:0xf bank_mask:0xf bound_ctrl:1
	s_waitcnt lgkmcnt(9)
	v_pk_mul_f32 v[66:67], v[76:77], v[28:29] op_sel_hi:[1,0]
	v_pk_mul_f32 v[68:69], v[76:77], v[28:29] op_sel:[0,1]
	v_pk_mul_f32 v[70:71], v[76:77], v[30:31] op_sel_hi:[1,0]
	v_pk_mul_f32 v[72:73], v[76:77], v[30:31] op_sel:[0,1]
	v_pk_fma_f32 v[66:67], v[32:33], v[24:25], v[66:67] op_sel_hi:[1,0,1]
	v_pk_fma_f32 v[68:69], v[32:33], v[24:25], v[68:69] op_sel:[0,1,0]
	v_pk_fma_f32 v[70:71], v[32:33], v[26:27], v[70:71] op_sel_hi:[1,0,1]
	v_pk_fma_f32 v[72:73], v[32:33], v[26:27], v[72:73] op_sel:[0,1,0]
	v_pk_fma_f32 v[0:1], v[0:1], v[20:21], v[66:67] op_sel_hi:[1,0,1]
	v_pk_fma_f32 v[2:3], v[2:3], v[20:21], v[68:69] op_sel:[0,1,0]
	v_pk_fma_f32 v[4:5], v[4:5], v[22:23], v[70:71] op_sel_hi:[1,0,1]
	v_pk_fma_f32 v[6:7], v[6:7], v[22:23], v[72:73] op_sel:[0,1,0]
	ds_write_b32 v84, v36 offset:2560
	ds_write_b32 v84, v76 offset:14848
	s_waitcnt lgkmcnt(7)
	v_pk_mul_f32 v[8:9], v[0:1], v[40:41] op_sel_hi:[1,0]
	v_pk_mul_f32 v[10:11], v[0:1], v[44:45] op_sel_hi:[1,0]
	ds_read_b128 v[12:15], v80 offset:34560
	v_pk_fma_f32 v[8:9], v[2:3], v[40:41], v[8:9] op_sel:[0,1,0]
	v_pk_fma_f32 v[10:11], v[2:3], v[44:45], v[10:11] op_sel:[0,1,0]
	ds_read_b128 v[16:19], v80 offset:33792
	v_pk_fma_f32 v[8:9], v[4:5], v[42:43], v[8:9] op_sel_hi:[1,0,1]
	v_pk_fma_f32 v[10:11], v[4:5], v[46:47], v[10:11] op_sel_hi:[1,0,1]
	ds_read_b128 v[20:23], v80 offset:34048
	v_pk_fma_f32 v[8:9], v[6:7], v[42:43], v[8:9] op_sel:[0,1,0]
	v_pk_fma_f32 v[10:11], v[6:7], v[46:47], v[10:11] op_sel:[0,1,0]
	ds_read_b128 v[24:27], v80 offset:34304
	v_add_f32_dpp v74, v9, v8 row_ror:8 row_mask:0xf bank_mask:0xf bound_ctrl:1
	v_add_f32_dpp v75, v11, v10 row_ror:8 row_mask:0xf bank_mask:0xf bound_ctrl:1
	ds_read_b128 v[28:31], v80 offset:34816
	v_add_f32_dpp v74, v74, v74 quad_perm:[1,0,3,2] row_mask:0xf bank_mask:0xf bound_ctrl:1
	v_add_f32_dpp v75, v75, v75 quad_perm:[1,0,3,2] row_mask:0xf bank_mask:0xf bound_ctrl:1
	ds_read_b32 v32, v81 offset:35072
	v_add_f32_dpp v74, v74, v74 quad_perm:[2,3,0,1] row_mask:0xf bank_mask:0xf bound_ctrl:1
	v_add_f32_dpp v75, v75, v75 quad_perm:[2,3,0,1] row_mask:0xf bank_mask:0xf bound_ctrl:1
	ds_read_b32 v33, v82 offset:35072
	v_add_f32_dpp v76, v74, v74 row_half_mirror row_mask:0xf bank_mask:0xf bound_ctrl:1
	v_add_f32_dpp v64, v75, v75 row_half_mirror row_mask:0xf bank_mask:0xf bound_ctrl:1
	s_nop 0
	v_mov_b32_dpp v77, v76 row_ror:8 row_mask:0xf bank_mask:0xf bound_ctrl:1
	s_waitcnt lgkmcnt(9)
	v_pk_mul_f32 v[66:67], v[76:77], v[56:57] op_sel_hi:[1,0]
	v_pk_mul_f32 v[68:69], v[76:77], v[56:57] op_sel:[0,1]
	v_pk_mul_f32 v[70:71], v[76:77], v[58:59] op_sel_hi:[1,0]
	v_pk_mul_f32 v[72:73], v[76:77], v[58:59] op_sel:[0,1]
	v_pk_fma_f32 v[66:67], v[60:61], v[52:53], v[66:67] op_sel_hi:[1,0,1]
	v_pk_fma_f32 v[68:69], v[60:61], v[52:53], v[68:69] op_sel:[0,1,0]
	v_pk_fma_f32 v[70:71], v[60:61], v[54:55], v[70:71] op_sel_hi:[1,0,1]
	v_pk_fma_f32 v[72:73], v[60:61], v[54:55], v[72:73] op_sel:[0,1,0]
	v_pk_fma_f32 v[0:1], v[0:1], v[48:49], v[66:67] op_sel_hi:[1,0,1]
	v_pk_fma_f32 v[2:3], v[2:3], v[48:49], v[68:69] op_sel:[0,1,0]
	v_pk_fma_f32 v[4:5], v[4:5], v[50:51], v[70:71] op_sel_hi:[1,0,1]
	v_pk_fma_f32 v[6:7], v[6:7], v[50:51], v[72:73] op_sel:[0,1,0]
	ds_write_b32 v84, v64 offset:2688
	ds_write_b32 v84, v76 offset:14976
	s_waitcnt lgkmcnt(7)
	v_pk_mul_f32 v[8:9], v[0:1], v[12:13] op_sel_hi:[1,0]
	v_pk_mul_f32 v[10:11], v[0:1], v[16:17] op_sel_hi:[1,0]
	ds_read_b128 v[40:43], v80 offset:36096
	v_pk_fma_f32 v[8:9], v[2:3], v[12:13], v[8:9] op_sel:[0,1,0]
	v_pk_fma_f32 v[10:11], v[2:3], v[16:17], v[10:11] op_sel:[0,1,0]
	ds_read_b128 v[44:47], v80 offset:35328
	v_pk_fma_f32 v[8:9], v[4:5], v[14:15], v[8:9] op_sel_hi:[1,0,1]
	v_pk_fma_f32 v[10:11], v[4:5], v[18:19], v[10:11] op_sel_hi:[1,0,1]
	ds_read_b128 v[48:51], v80 offset:35584
	v_pk_fma_f32 v[8:9], v[6:7], v[14:15], v[8:9] op_sel:[0,1,0]
	v_pk_fma_f32 v[10:11], v[6:7], v[18:19], v[10:11] op_sel:[0,1,0]
	ds_read_b128 v[52:55], v80 offset:35840
	v_add_f32_dpp v74, v9, v8 row_ror:8 row_mask:0xf bank_mask:0xf bound_ctrl:1
	v_add_f32_dpp v75, v11, v10 row_ror:8 row_mask:0xf bank_mask:0xf bound_ctrl:1
	ds_read_b128 v[56:59], v80 offset:36352
	v_add_f32_dpp v74, v74, v74 quad_perm:[1,0,3,2] row_mask:0xf bank_mask:0xf bound_ctrl:1
	v_add_f32_dpp v75, v75, v75 quad_perm:[1,0,3,2] row_mask:0xf bank_mask:0xf bound_ctrl:1
	ds_read_b32 v60, v81 offset:36608
	v_add_f32_dpp v74, v74, v74 quad_perm:[2,3,0,1] row_mask:0xf bank_mask:0xf bound_ctrl:1
	v_add_f32_dpp v75, v75, v75 quad_perm:[2,3,0,1] row_mask:0xf bank_mask:0xf bound_ctrl:1
	ds_read_b32 v61, v82 offset:36608
	v_add_f32_dpp v76, v74, v74 row_half_mirror row_mask:0xf bank_mask:0xf bound_ctrl:1
	v_add_f32_dpp v36, v75, v75 row_half_mirror row_mask:0xf bank_mask:0xf bound_ctrl:1
	s_nop 0
	v_mov_b32_dpp v77, v76 row_ror:8 row_mask:0xf bank_mask:0xf bound_ctrl:1
	s_waitcnt lgkmcnt(9)
	v_pk_mul_f32 v[66:67], v[76:77], v[28:29] op_sel_hi:[1,0]
	v_pk_mul_f32 v[68:69], v[76:77], v[28:29] op_sel:[0,1]
	v_pk_mul_f32 v[70:71], v[76:77], v[30:31] op_sel_hi:[1,0]
	v_pk_mul_f32 v[72:73], v[76:77], v[30:31] op_sel:[0,1]
	v_pk_fma_f32 v[66:67], v[32:33], v[24:25], v[66:67] op_sel_hi:[1,0,1]
	v_pk_fma_f32 v[68:69], v[32:33], v[24:25], v[68:69] op_sel:[0,1,0]
	v_pk_fma_f32 v[70:71], v[32:33], v[26:27], v[70:71] op_sel_hi:[1,0,1]
	v_pk_fma_f32 v[72:73], v[32:33], v[26:27], v[72:73] op_sel:[0,1,0]
	v_pk_fma_f32 v[0:1], v[0:1], v[20:21], v[66:67] op_sel_hi:[1,0,1]
	v_pk_fma_f32 v[2:3], v[2:3], v[20:21], v[68:69] op_sel:[0,1,0]
	v_pk_fma_f32 v[4:5], v[4:5], v[22:23], v[70:71] op_sel_hi:[1,0,1]
	v_pk_fma_f32 v[6:7], v[6:7], v[22:23], v[72:73] op_sel:[0,1,0]
	ds_write_b32 v84, v36 offset:2816
	ds_write_b32 v84, v76 offset:15104
	s_waitcnt lgkmcnt(7)
	v_pk_mul_f32 v[8:9], v[0:1], v[40:41] op_sel_hi:[1,0]
	v_pk_mul_f32 v[10:11], v[0:1], v[44:45] op_sel_hi:[1,0]
	ds_read_b128 v[12:15], v80 offset:37632
	v_pk_fma_f32 v[8:9], v[2:3], v[40:41], v[8:9] op_sel:[0,1,0]
	v_pk_fma_f32 v[10:11], v[2:3], v[44:45], v[10:11] op_sel:[0,1,0]
	ds_read_b128 v[16:19], v80 offset:36864
	v_pk_fma_f32 v[8:9], v[4:5], v[42:43], v[8:9] op_sel_hi:[1,0,1]
	v_pk_fma_f32 v[10:11], v[4:5], v[46:47], v[10:11] op_sel_hi:[1,0,1]
	ds_read_b128 v[20:23], v80 offset:37120
	v_pk_fma_f32 v[8:9], v[6:7], v[42:43], v[8:9] op_sel:[0,1,0]
	v_pk_fma_f32 v[10:11], v[6:7], v[46:47], v[10:11] op_sel:[0,1,0]
	ds_read_b128 v[24:27], v80 offset:37376
	v_add_f32_dpp v74, v9, v8 row_ror:8 row_mask:0xf bank_mask:0xf bound_ctrl:1
	v_add_f32_dpp v75, v11, v10 row_ror:8 row_mask:0xf bank_mask:0xf bound_ctrl:1
	ds_read_b128 v[28:31], v80 offset:37888
	v_add_f32_dpp v74, v74, v74 quad_perm:[1,0,3,2] row_mask:0xf bank_mask:0xf bound_ctrl:1
	v_add_f32_dpp v75, v75, v75 quad_perm:[1,0,3,2] row_mask:0xf bank_mask:0xf bound_ctrl:1
	ds_read_b32 v32, v81 offset:38144
	v_add_f32_dpp v74, v74, v74 quad_perm:[2,3,0,1] row_mask:0xf bank_mask:0xf bound_ctrl:1
	v_add_f32_dpp v75, v75, v75 quad_perm:[2,3,0,1] row_mask:0xf bank_mask:0xf bound_ctrl:1
	ds_read_b32 v33, v82 offset:38144
	v_add_f32_dpp v76, v74, v74 row_half_mirror row_mask:0xf bank_mask:0xf bound_ctrl:1
	v_add_f32_dpp v64, v75, v75 row_half_mirror row_mask:0xf bank_mask:0xf bound_ctrl:1
	s_nop 0
	v_mov_b32_dpp v77, v76 row_ror:8 row_mask:0xf bank_mask:0xf bound_ctrl:1
	s_waitcnt lgkmcnt(9)
	v_pk_mul_f32 v[66:67], v[76:77], v[56:57] op_sel_hi:[1,0]
	v_pk_mul_f32 v[68:69], v[76:77], v[56:57] op_sel:[0,1]
	v_pk_mul_f32 v[70:71], v[76:77], v[58:59] op_sel_hi:[1,0]
	v_pk_mul_f32 v[72:73], v[76:77], v[58:59] op_sel:[0,1]
	v_pk_fma_f32 v[66:67], v[60:61], v[52:53], v[66:67] op_sel_hi:[1,0,1]
	v_pk_fma_f32 v[68:69], v[60:61], v[52:53], v[68:69] op_sel:[0,1,0]
	v_pk_fma_f32 v[70:71], v[60:61], v[54:55], v[70:71] op_sel_hi:[1,0,1]
	v_pk_fma_f32 v[72:73], v[60:61], v[54:55], v[72:73] op_sel:[0,1,0]
	v_pk_fma_f32 v[0:1], v[0:1], v[48:49], v[66:67] op_sel_hi:[1,0,1]
	v_pk_fma_f32 v[2:3], v[2:3], v[48:49], v[68:69] op_sel:[0,1,0]
	v_pk_fma_f32 v[4:5], v[4:5], v[50:51], v[70:71] op_sel_hi:[1,0,1]
	v_pk_fma_f32 v[6:7], v[6:7], v[50:51], v[72:73] op_sel:[0,1,0]
	ds_write_b32 v84, v64 offset:2944
	ds_write_b32 v84, v76 offset:15232
	s_waitcnt lgkmcnt(7)
	v_pk_mul_f32 v[8:9], v[0:1], v[12:13] op_sel_hi:[1,0]
	v_pk_mul_f32 v[10:11], v[0:1], v[16:17] op_sel_hi:[1,0]
	ds_read_b128 v[40:43], v80 offset:39168
	v_pk_fma_f32 v[8:9], v[2:3], v[12:13], v[8:9] op_sel:[0,1,0]
	v_pk_fma_f32 v[10:11], v[2:3], v[16:17], v[10:11] op_sel:[0,1,0]
	ds_read_b128 v[44:47], v80 offset:38400
	v_pk_fma_f32 v[8:9], v[4:5], v[14:15], v[8:9] op_sel_hi:[1,0,1]
	v_pk_fma_f32 v[10:11], v[4:5], v[18:19], v[10:11] op_sel_hi:[1,0,1]
	ds_read_b128 v[48:51], v80 offset:38656
	v_pk_fma_f32 v[8:9], v[6:7], v[14:15], v[8:9] op_sel:[0,1,0]
	v_pk_fma_f32 v[10:11], v[6:7], v[18:19], v[10:11] op_sel:[0,1,0]
	ds_read_b128 v[52:55], v80 offset:38912
	v_add_f32_dpp v74, v9, v8 row_ror:8 row_mask:0xf bank_mask:0xf bound_ctrl:1
	v_add_f32_dpp v75, v11, v10 row_ror:8 row_mask:0xf bank_mask:0xf bound_ctrl:1
	ds_read_b128 v[56:59], v80 offset:39424
	v_add_f32_dpp v74, v74, v74 quad_perm:[1,0,3,2] row_mask:0xf bank_mask:0xf bound_ctrl:1
	v_add_f32_dpp v75, v75, v75 quad_perm:[1,0,3,2] row_mask:0xf bank_mask:0xf bound_ctrl:1
	ds_read_b32 v60, v81 offset:39680
	v_add_f32_dpp v74, v74, v74 quad_perm:[2,3,0,1] row_mask:0xf bank_mask:0xf bound_ctrl:1
	v_add_f32_dpp v75, v75, v75 quad_perm:[2,3,0,1] row_mask:0xf bank_mask:0xf bound_ctrl:1
	ds_read_b32 v61, v82 offset:39680
	v_add_f32_dpp v76, v74, v74 row_half_mirror row_mask:0xf bank_mask:0xf bound_ctrl:1
	v_add_f32_dpp v36, v75, v75 row_half_mirror row_mask:0xf bank_mask:0xf bound_ctrl:1
	s_nop 0
	v_mov_b32_dpp v77, v76 row_ror:8 row_mask:0xf bank_mask:0xf bound_ctrl:1
	s_waitcnt lgkmcnt(9)
	v_pk_mul_f32 v[66:67], v[76:77], v[28:29] op_sel_hi:[1,0]
	v_pk_mul_f32 v[68:69], v[76:77], v[28:29] op_sel:[0,1]
	v_pk_mul_f32 v[70:71], v[76:77], v[30:31] op_sel_hi:[1,0]
	v_pk_mul_f32 v[72:73], v[76:77], v[30:31] op_sel:[0,1]
	v_pk_fma_f32 v[66:67], v[32:33], v[24:25], v[66:67] op_sel_hi:[1,0,1]
	v_pk_fma_f32 v[68:69], v[32:33], v[24:25], v[68:69] op_sel:[0,1,0]
	v_pk_fma_f32 v[70:71], v[32:33], v[26:27], v[70:71] op_sel_hi:[1,0,1]
	v_pk_fma_f32 v[72:73], v[32:33], v[26:27], v[72:73] op_sel:[0,1,0]
	v_pk_fma_f32 v[0:1], v[0:1], v[20:21], v[66:67] op_sel_hi:[1,0,1]
	v_pk_fma_f32 v[2:3], v[2:3], v[20:21], v[68:69] op_sel:[0,1,0]
	v_pk_fma_f32 v[4:5], v[4:5], v[22:23], v[70:71] op_sel_hi:[1,0,1]
	v_pk_fma_f32 v[6:7], v[6:7], v[22:23], v[72:73] op_sel:[0,1,0]
	ds_write_b32 v84, v36 offset:3072
	ds_write_b32 v84, v76 offset:15360
	s_waitcnt lgkmcnt(7)
	v_pk_mul_f32 v[8:9], v[0:1], v[40:41] op_sel_hi:[1,0]
	v_pk_mul_f32 v[10:11], v[0:1], v[44:45] op_sel_hi:[1,0]
	ds_read_b128 v[12:15], v80 offset:40704
	v_pk_fma_f32 v[8:9], v[2:3], v[40:41], v[8:9] op_sel:[0,1,0]
	v_pk_fma_f32 v[10:11], v[2:3], v[44:45], v[10:11] op_sel:[0,1,0]
	ds_read_b128 v[16:19], v80 offset:39936
	v_pk_fma_f32 v[8:9], v[4:5], v[42:43], v[8:9] op_sel_hi:[1,0,1]
	v_pk_fma_f32 v[10:11], v[4:5], v[46:47], v[10:11] op_sel_hi:[1,0,1]
	ds_read_b128 v[20:23], v80 offset:40192
	v_pk_fma_f32 v[8:9], v[6:7], v[42:43], v[8:9] op_sel:[0,1,0]
	v_pk_fma_f32 v[10:11], v[6:7], v[46:47], v[10:11] op_sel:[0,1,0]
	ds_read_b128 v[24:27], v80 offset:40448
	v_add_f32_dpp v74, v9, v8 row_ror:8 row_mask:0xf bank_mask:0xf bound_ctrl:1
	v_add_f32_dpp v75, v11, v10 row_ror:8 row_mask:0xf bank_mask:0xf bound_ctrl:1
	ds_read_b128 v[28:31], v80 offset:40960
	v_add_f32_dpp v74, v74, v74 quad_perm:[1,0,3,2] row_mask:0xf bank_mask:0xf bound_ctrl:1
	v_add_f32_dpp v75, v75, v75 quad_perm:[1,0,3,2] row_mask:0xf bank_mask:0xf bound_ctrl:1
	ds_read_b32 v32, v81 offset:41216
	v_add_f32_dpp v74, v74, v74 quad_perm:[2,3,0,1] row_mask:0xf bank_mask:0xf bound_ctrl:1
	v_add_f32_dpp v75, v75, v75 quad_perm:[2,3,0,1] row_mask:0xf bank_mask:0xf bound_ctrl:1
	ds_read_b32 v33, v82 offset:41216
	v_add_f32_dpp v76, v74, v74 row_half_mirror row_mask:0xf bank_mask:0xf bound_ctrl:1
	v_add_f32_dpp v64, v75, v75 row_half_mirror row_mask:0xf bank_mask:0xf bound_ctrl:1
	s_nop 0
	v_mov_b32_dpp v77, v76 row_ror:8 row_mask:0xf bank_mask:0xf bound_ctrl:1
	s_waitcnt lgkmcnt(9)
	v_pk_mul_f32 v[66:67], v[76:77], v[56:57] op_sel_hi:[1,0]
	v_pk_mul_f32 v[68:69], v[76:77], v[56:57] op_sel:[0,1]
	v_pk_mul_f32 v[70:71], v[76:77], v[58:59] op_sel_hi:[1,0]
	v_pk_mul_f32 v[72:73], v[76:77], v[58:59] op_sel:[0,1]
	v_pk_fma_f32 v[66:67], v[60:61], v[52:53], v[66:67] op_sel_hi:[1,0,1]
	v_pk_fma_f32 v[68:69], v[60:61], v[52:53], v[68:69] op_sel:[0,1,0]
	v_pk_fma_f32 v[70:71], v[60:61], v[54:55], v[70:71] op_sel_hi:[1,0,1]
	v_pk_fma_f32 v[72:73], v[60:61], v[54:55], v[72:73] op_sel:[0,1,0]
	v_pk_fma_f32 v[0:1], v[0:1], v[48:49], v[66:67] op_sel_hi:[1,0,1]
	v_pk_fma_f32 v[2:3], v[2:3], v[48:49], v[68:69] op_sel:[0,1,0]
	v_pk_fma_f32 v[4:5], v[4:5], v[50:51], v[70:71] op_sel_hi:[1,0,1]
	v_pk_fma_f32 v[6:7], v[6:7], v[50:51], v[72:73] op_sel:[0,1,0]
	ds_write_b32 v84, v64 offset:3200
	ds_write_b32 v84, v76 offset:15488
	s_waitcnt lgkmcnt(7)
	v_pk_mul_f32 v[8:9], v[0:1], v[12:13] op_sel_hi:[1,0]
	v_pk_mul_f32 v[10:11], v[0:1], v[16:17] op_sel_hi:[1,0]
	ds_read_b128 v[40:43], v80 offset:42240
	v_pk_fma_f32 v[8:9], v[2:3], v[12:13], v[8:9] op_sel:[0,1,0]
	v_pk_fma_f32 v[10:11], v[2:3], v[16:17], v[10:11] op_sel:[0,1,0]
	ds_read_b128 v[44:47], v80 offset:41472
	v_pk_fma_f32 v[8:9], v[4:5], v[14:15], v[8:9] op_sel_hi:[1,0,1]
	v_pk_fma_f32 v[10:11], v[4:5], v[18:19], v[10:11] op_sel_hi:[1,0,1]
	ds_read_b128 v[48:51], v80 offset:41728
	v_pk_fma_f32 v[8:9], v[6:7], v[14:15], v[8:9] op_sel:[0,1,0]
	v_pk_fma_f32 v[10:11], v[6:7], v[18:19], v[10:11] op_sel:[0,1,0]
	ds_read_b128 v[52:55], v80 offset:41984
	v_add_f32_dpp v74, v9, v8 row_ror:8 row_mask:0xf bank_mask:0xf bound_ctrl:1
	v_add_f32_dpp v75, v11, v10 row_ror:8 row_mask:0xf bank_mask:0xf bound_ctrl:1
	ds_read_b128 v[56:59], v80 offset:42496
	v_add_f32_dpp v74, v74, v74 quad_perm:[1,0,3,2] row_mask:0xf bank_mask:0xf bound_ctrl:1
	v_add_f32_dpp v75, v75, v75 quad_perm:[1,0,3,2] row_mask:0xf bank_mask:0xf bound_ctrl:1
	ds_read_b32 v60, v81 offset:42752
	v_add_f32_dpp v74, v74, v74 quad_perm:[2,3,0,1] row_mask:0xf bank_mask:0xf bound_ctrl:1
	v_add_f32_dpp v75, v75, v75 quad_perm:[2,3,0,1] row_mask:0xf bank_mask:0xf bound_ctrl:1
	ds_read_b32 v61, v82 offset:42752
	v_add_f32_dpp v76, v74, v74 row_half_mirror row_mask:0xf bank_mask:0xf bound_ctrl:1
	v_add_f32_dpp v36, v75, v75 row_half_mirror row_mask:0xf bank_mask:0xf bound_ctrl:1
	s_nop 0
	v_mov_b32_dpp v77, v76 row_ror:8 row_mask:0xf bank_mask:0xf bound_ctrl:1
	s_waitcnt lgkmcnt(9)
	v_pk_mul_f32 v[66:67], v[76:77], v[28:29] op_sel_hi:[1,0]
	v_pk_mul_f32 v[68:69], v[76:77], v[28:29] op_sel:[0,1]
	v_pk_mul_f32 v[70:71], v[76:77], v[30:31] op_sel_hi:[1,0]
	v_pk_mul_f32 v[72:73], v[76:77], v[30:31] op_sel:[0,1]
	v_pk_fma_f32 v[66:67], v[32:33], v[24:25], v[66:67] op_sel_hi:[1,0,1]
	v_pk_fma_f32 v[68:69], v[32:33], v[24:25], v[68:69] op_sel:[0,1,0]
	v_pk_fma_f32 v[70:71], v[32:33], v[26:27], v[70:71] op_sel_hi:[1,0,1]
	v_pk_fma_f32 v[72:73], v[32:33], v[26:27], v[72:73] op_sel:[0,1,0]
	v_pk_fma_f32 v[0:1], v[0:1], v[20:21], v[66:67] op_sel_hi:[1,0,1]
	v_pk_fma_f32 v[2:3], v[2:3], v[20:21], v[68:69] op_sel:[0,1,0]
	v_pk_fma_f32 v[4:5], v[4:5], v[22:23], v[70:71] op_sel_hi:[1,0,1]
	v_pk_fma_f32 v[6:7], v[6:7], v[22:23], v[72:73] op_sel:[0,1,0]
	ds_write_b32 v84, v36 offset:3328
	ds_write_b32 v84, v76 offset:15616
	s_waitcnt lgkmcnt(7)
	v_pk_mul_f32 v[8:9], v[0:1], v[40:41] op_sel_hi:[1,0]
	v_pk_mul_f32 v[10:11], v[0:1], v[44:45] op_sel_hi:[1,0]
	ds_read_b128 v[12:15], v80 offset:43776
	v_pk_fma_f32 v[8:9], v[2:3], v[40:41], v[8:9] op_sel:[0,1,0]
	v_pk_fma_f32 v[10:11], v[2:3], v[44:45], v[10:11] op_sel:[0,1,0]
	ds_read_b128 v[16:19], v80 offset:43008
	v_pk_fma_f32 v[8:9], v[4:5], v[42:43], v[8:9] op_sel_hi:[1,0,1]
	v_pk_fma_f32 v[10:11], v[4:5], v[46:47], v[10:11] op_sel_hi:[1,0,1]
	ds_read_b128 v[20:23], v80 offset:43264
	v_pk_fma_f32 v[8:9], v[6:7], v[42:43], v[8:9] op_sel:[0,1,0]
	v_pk_fma_f32 v[10:11], v[6:7], v[46:47], v[10:11] op_sel:[0,1,0]
	ds_read_b128 v[24:27], v80 offset:43520
	v_add_f32_dpp v74, v9, v8 row_ror:8 row_mask:0xf bank_mask:0xf bound_ctrl:1
	v_add_f32_dpp v75, v11, v10 row_ror:8 row_mask:0xf bank_mask:0xf bound_ctrl:1
	ds_read_b128 v[28:31], v80 offset:44032
	v_add_f32_dpp v74, v74, v74 quad_perm:[1,0,3,2] row_mask:0xf bank_mask:0xf bound_ctrl:1
	v_add_f32_dpp v75, v75, v75 quad_perm:[1,0,3,2] row_mask:0xf bank_mask:0xf bound_ctrl:1
	ds_read_b32 v32, v81 offset:44288
	v_add_f32_dpp v74, v74, v74 quad_perm:[2,3,0,1] row_mask:0xf bank_mask:0xf bound_ctrl:1
	v_add_f32_dpp v75, v75, v75 quad_perm:[2,3,0,1] row_mask:0xf bank_mask:0xf bound_ctrl:1
	ds_read_b32 v33, v82 offset:44288
	v_add_f32_dpp v76, v74, v74 row_half_mirror row_mask:0xf bank_mask:0xf bound_ctrl:1
	v_add_f32_dpp v64, v75, v75 row_half_mirror row_mask:0xf bank_mask:0xf bound_ctrl:1
	s_nop 0
	v_mov_b32_dpp v77, v76 row_ror:8 row_mask:0xf bank_mask:0xf bound_ctrl:1
	s_waitcnt lgkmcnt(9)
	v_pk_mul_f32 v[66:67], v[76:77], v[56:57] op_sel_hi:[1,0]
	v_pk_mul_f32 v[68:69], v[76:77], v[56:57] op_sel:[0,1]
	v_pk_mul_f32 v[70:71], v[76:77], v[58:59] op_sel_hi:[1,0]
	v_pk_mul_f32 v[72:73], v[76:77], v[58:59] op_sel:[0,1]
	v_pk_fma_f32 v[66:67], v[60:61], v[52:53], v[66:67] op_sel_hi:[1,0,1]
	v_pk_fma_f32 v[68:69], v[60:61], v[52:53], v[68:69] op_sel:[0,1,0]
	v_pk_fma_f32 v[70:71], v[60:61], v[54:55], v[70:71] op_sel_hi:[1,0,1]
	v_pk_fma_f32 v[72:73], v[60:61], v[54:55], v[72:73] op_sel:[0,1,0]
	v_pk_fma_f32 v[0:1], v[0:1], v[48:49], v[66:67] op_sel_hi:[1,0,1]
	v_pk_fma_f32 v[2:3], v[2:3], v[48:49], v[68:69] op_sel:[0,1,0]
	v_pk_fma_f32 v[4:5], v[4:5], v[50:51], v[70:71] op_sel_hi:[1,0,1]
	v_pk_fma_f32 v[6:7], v[6:7], v[50:51], v[72:73] op_sel:[0,1,0]
	ds_write_b32 v84, v64 offset:3456
	ds_write_b32 v84, v76 offset:15744
	s_waitcnt lgkmcnt(7)
	v_pk_mul_f32 v[8:9], v[0:1], v[12:13] op_sel_hi:[1,0]
	v_pk_mul_f32 v[10:11], v[0:1], v[16:17] op_sel_hi:[1,0]
	ds_read_b128 v[40:43], v80 offset:45312
	v_pk_fma_f32 v[8:9], v[2:3], v[12:13], v[8:9] op_sel:[0,1,0]
	v_pk_fma_f32 v[10:11], v[2:3], v[16:17], v[10:11] op_sel:[0,1,0]
	ds_read_b128 v[44:47], v80 offset:44544
	v_pk_fma_f32 v[8:9], v[4:5], v[14:15], v[8:9] op_sel_hi:[1,0,1]
	v_pk_fma_f32 v[10:11], v[4:5], v[18:19], v[10:11] op_sel_hi:[1,0,1]
	ds_read_b128 v[48:51], v80 offset:44800
	v_pk_fma_f32 v[8:9], v[6:7], v[14:15], v[8:9] op_sel:[0,1,0]
	v_pk_fma_f32 v[10:11], v[6:7], v[18:19], v[10:11] op_sel:[0,1,0]
	ds_read_b128 v[52:55], v80 offset:45056
	v_add_f32_dpp v74, v9, v8 row_ror:8 row_mask:0xf bank_mask:0xf bound_ctrl:1
	v_add_f32_dpp v75, v11, v10 row_ror:8 row_mask:0xf bank_mask:0xf bound_ctrl:1
	ds_read_b128 v[56:59], v80 offset:45568
	v_add_f32_dpp v74, v74, v74 quad_perm:[1,0,3,2] row_mask:0xf bank_mask:0xf bound_ctrl:1
	v_add_f32_dpp v75, v75, v75 quad_perm:[1,0,3,2] row_mask:0xf bank_mask:0xf bound_ctrl:1
	ds_read_b32 v60, v81 offset:45824
	v_add_f32_dpp v74, v74, v74 quad_perm:[2,3,0,1] row_mask:0xf bank_mask:0xf bound_ctrl:1
	v_add_f32_dpp v75, v75, v75 quad_perm:[2,3,0,1] row_mask:0xf bank_mask:0xf bound_ctrl:1
	ds_read_b32 v61, v82 offset:45824
	v_add_f32_dpp v76, v74, v74 row_half_mirror row_mask:0xf bank_mask:0xf bound_ctrl:1
	v_add_f32_dpp v36, v75, v75 row_half_mirror row_mask:0xf bank_mask:0xf bound_ctrl:1
	s_nop 0
	v_mov_b32_dpp v77, v76 row_ror:8 row_mask:0xf bank_mask:0xf bound_ctrl:1
	s_waitcnt lgkmcnt(9)
	v_pk_mul_f32 v[66:67], v[76:77], v[28:29] op_sel_hi:[1,0]
	v_pk_mul_f32 v[68:69], v[76:77], v[28:29] op_sel:[0,1]
	v_pk_mul_f32 v[70:71], v[76:77], v[30:31] op_sel_hi:[1,0]
	v_pk_mul_f32 v[72:73], v[76:77], v[30:31] op_sel:[0,1]
	v_pk_fma_f32 v[66:67], v[32:33], v[24:25], v[66:67] op_sel_hi:[1,0,1]
	v_pk_fma_f32 v[68:69], v[32:33], v[24:25], v[68:69] op_sel:[0,1,0]
	v_pk_fma_f32 v[70:71], v[32:33], v[26:27], v[70:71] op_sel_hi:[1,0,1]
	v_pk_fma_f32 v[72:73], v[32:33], v[26:27], v[72:73] op_sel:[0,1,0]
	v_pk_fma_f32 v[0:1], v[0:1], v[20:21], v[66:67] op_sel_hi:[1,0,1]
	v_pk_fma_f32 v[2:3], v[2:3], v[20:21], v[68:69] op_sel:[0,1,0]
	v_pk_fma_f32 v[4:5], v[4:5], v[22:23], v[70:71] op_sel_hi:[1,0,1]
	v_pk_fma_f32 v[6:7], v[6:7], v[22:23], v[72:73] op_sel:[0,1,0]
	ds_write_b32 v84, v36 offset:3584
	ds_write_b32 v84, v76 offset:15872
	s_waitcnt lgkmcnt(7)
	v_pk_mul_f32 v[8:9], v[0:1], v[40:41] op_sel_hi:[1,0]
	v_pk_mul_f32 v[10:11], v[0:1], v[44:45] op_sel_hi:[1,0]
	ds_read_b128 v[12:15], v80 offset:46848
	v_pk_fma_f32 v[8:9], v[2:3], v[40:41], v[8:9] op_sel:[0,1,0]
	v_pk_fma_f32 v[10:11], v[2:3], v[44:45], v[10:11] op_sel:[0,1,0]
	ds_read_b128 v[16:19], v80 offset:46080
	v_pk_fma_f32 v[8:9], v[4:5], v[42:43], v[8:9] op_sel_hi:[1,0,1]
	v_pk_fma_f32 v[10:11], v[4:5], v[46:47], v[10:11] op_sel_hi:[1,0,1]
	ds_read_b128 v[20:23], v80 offset:46336
	v_pk_fma_f32 v[8:9], v[6:7], v[42:43], v[8:9] op_sel:[0,1,0]
	v_pk_fma_f32 v[10:11], v[6:7], v[46:47], v[10:11] op_sel:[0,1,0]
	ds_read_b128 v[24:27], v80 offset:46592
	v_add_f32_dpp v74, v9, v8 row_ror:8 row_mask:0xf bank_mask:0xf bound_ctrl:1
	v_add_f32_dpp v75, v11, v10 row_ror:8 row_mask:0xf bank_mask:0xf bound_ctrl:1
	ds_read_b128 v[28:31], v80 offset:47104
	v_add_f32_dpp v74, v74, v74 quad_perm:[1,0,3,2] row_mask:0xf bank_mask:0xf bound_ctrl:1
	v_add_f32_dpp v75, v75, v75 quad_perm:[1,0,3,2] row_mask:0xf bank_mask:0xf bound_ctrl:1
	ds_read_b32 v32, v81 offset:47360
	v_add_f32_dpp v74, v74, v74 quad_perm:[2,3,0,1] row_mask:0xf bank_mask:0xf bound_ctrl:1
	v_add_f32_dpp v75, v75, v75 quad_perm:[2,3,0,1] row_mask:0xf bank_mask:0xf bound_ctrl:1
	ds_read_b32 v33, v82 offset:47360
	v_add_f32_dpp v76, v74, v74 row_half_mirror row_mask:0xf bank_mask:0xf bound_ctrl:1
	v_add_f32_dpp v64, v75, v75 row_half_mirror row_mask:0xf bank_mask:0xf bound_ctrl:1
	s_nop 0
	v_mov_b32_dpp v77, v76 row_ror:8 row_mask:0xf bank_mask:0xf bound_ctrl:1
	s_waitcnt lgkmcnt(9)
	v_pk_mul_f32 v[66:67], v[76:77], v[56:57] op_sel_hi:[1,0]
	v_pk_mul_f32 v[68:69], v[76:77], v[56:57] op_sel:[0,1]
	v_pk_mul_f32 v[70:71], v[76:77], v[58:59] op_sel_hi:[1,0]
	v_pk_mul_f32 v[72:73], v[76:77], v[58:59] op_sel:[0,1]
	v_pk_fma_f32 v[66:67], v[60:61], v[52:53], v[66:67] op_sel_hi:[1,0,1]
	v_pk_fma_f32 v[68:69], v[60:61], v[52:53], v[68:69] op_sel:[0,1,0]
	v_pk_fma_f32 v[70:71], v[60:61], v[54:55], v[70:71] op_sel_hi:[1,0,1]
	v_pk_fma_f32 v[72:73], v[60:61], v[54:55], v[72:73] op_sel:[0,1,0]
	v_pk_fma_f32 v[0:1], v[0:1], v[48:49], v[66:67] op_sel_hi:[1,0,1]
	v_pk_fma_f32 v[2:3], v[2:3], v[48:49], v[68:69] op_sel:[0,1,0]
	v_pk_fma_f32 v[4:5], v[4:5], v[50:51], v[70:71] op_sel_hi:[1,0,1]
	v_pk_fma_f32 v[6:7], v[6:7], v[50:51], v[72:73] op_sel:[0,1,0]
	ds_write_b32 v84, v64 offset:3712
	ds_write_b32 v84, v76 offset:16000
	s_waitcnt lgkmcnt(7)
	v_pk_mul_f32 v[8:9], v[0:1], v[12:13] op_sel_hi:[1,0]
	v_pk_mul_f32 v[10:11], v[0:1], v[16:17] op_sel_hi:[1,0]
	ds_read_b128 v[40:43], v80 offset:48384
	v_pk_fma_f32 v[8:9], v[2:3], v[12:13], v[8:9] op_sel:[0,1,0]
	v_pk_fma_f32 v[10:11], v[2:3], v[16:17], v[10:11] op_sel:[0,1,0]
	ds_read_b128 v[44:47], v80 offset:47616
	v_pk_fma_f32 v[8:9], v[4:5], v[14:15], v[8:9] op_sel_hi:[1,0,1]
	v_pk_fma_f32 v[10:11], v[4:5], v[18:19], v[10:11] op_sel_hi:[1,0,1]
	ds_read_b128 v[48:51], v80 offset:47872
	v_pk_fma_f32 v[8:9], v[6:7], v[14:15], v[8:9] op_sel:[0,1,0]
	v_pk_fma_f32 v[10:11], v[6:7], v[18:19], v[10:11] op_sel:[0,1,0]
	ds_read_b128 v[52:55], v80 offset:48128
	v_add_f32_dpp v74, v9, v8 row_ror:8 row_mask:0xf bank_mask:0xf bound_ctrl:1
	v_add_f32_dpp v75, v11, v10 row_ror:8 row_mask:0xf bank_mask:0xf bound_ctrl:1
	ds_read_b128 v[56:59], v80 offset:48640
	v_add_f32_dpp v74, v74, v74 quad_perm:[1,0,3,2] row_mask:0xf bank_mask:0xf bound_ctrl:1
	v_add_f32_dpp v75, v75, v75 quad_perm:[1,0,3,2] row_mask:0xf bank_mask:0xf bound_ctrl:1
	ds_read_b32 v60, v81 offset:48896
	v_add_f32_dpp v74, v74, v74 quad_perm:[2,3,0,1] row_mask:0xf bank_mask:0xf bound_ctrl:1
	v_add_f32_dpp v75, v75, v75 quad_perm:[2,3,0,1] row_mask:0xf bank_mask:0xf bound_ctrl:1
	ds_read_b32 v61, v82 offset:48896
	v_add_f32_dpp v76, v74, v74 row_half_mirror row_mask:0xf bank_mask:0xf bound_ctrl:1
	v_add_f32_dpp v36, v75, v75 row_half_mirror row_mask:0xf bank_mask:0xf bound_ctrl:1
	s_nop 0
	v_mov_b32_dpp v77, v76 row_ror:8 row_mask:0xf bank_mask:0xf bound_ctrl:1
	s_waitcnt lgkmcnt(9)
	v_pk_mul_f32 v[66:67], v[76:77], v[28:29] op_sel_hi:[1,0]
	v_pk_mul_f32 v[68:69], v[76:77], v[28:29] op_sel:[0,1]
	v_pk_mul_f32 v[70:71], v[76:77], v[30:31] op_sel_hi:[1,0]
	v_pk_mul_f32 v[72:73], v[76:77], v[30:31] op_sel:[0,1]
	v_pk_fma_f32 v[66:67], v[32:33], v[24:25], v[66:67] op_sel_hi:[1,0,1]
	v_pk_fma_f32 v[68:69], v[32:33], v[24:25], v[68:69] op_sel:[0,1,0]
	v_pk_fma_f32 v[70:71], v[32:33], v[26:27], v[70:71] op_sel_hi:[1,0,1]
	v_pk_fma_f32 v[72:73], v[32:33], v[26:27], v[72:73] op_sel:[0,1,0]
	v_pk_fma_f32 v[0:1], v[0:1], v[20:21], v[66:67] op_sel_hi:[1,0,1]
	v_pk_fma_f32 v[2:3], v[2:3], v[20:21], v[68:69] op_sel:[0,1,0]
	v_pk_fma_f32 v[4:5], v[4:5], v[22:23], v[70:71] op_sel_hi:[1,0,1]
	v_pk_fma_f32 v[6:7], v[6:7], v[22:23], v[72:73] op_sel:[0,1,0]
	ds_write_b32 v84, v36 offset:3840
	ds_write_b32 v84, v76 offset:16128
	s_waitcnt lgkmcnt(7)
	v_pk_mul_f32 v[8:9], v[0:1], v[40:41] op_sel_hi:[1,0]
	v_pk_mul_f32 v[10:11], v[0:1], v[44:45] op_sel_hi:[1,0]
	v_pk_fma_f32 v[8:9], v[2:3], v[40:41], v[8:9] op_sel:[0,1,0]
	v_pk_fma_f32 v[10:11], v[2:3], v[44:45], v[10:11] op_sel:[0,1,0]
	v_pk_fma_f32 v[8:9], v[4:5], v[42:43], v[8:9] op_sel_hi:[1,0,1]
	v_pk_fma_f32 v[10:11], v[4:5], v[46:47], v[10:11] op_sel_hi:[1,0,1]
	v_pk_fma_f32 v[8:9], v[6:7], v[42:43], v[8:9] op_sel:[0,1,0]
	v_pk_fma_f32 v[10:11], v[6:7], v[46:47], v[10:11] op_sel:[0,1,0]
	s_nop 0
	v_add_f32_dpp v74, v9, v8 row_ror:8 row_mask:0xf bank_mask:0xf bound_ctrl:1
	v_add_f32_dpp v75, v11, v10 row_ror:8 row_mask:0xf bank_mask:0xf bound_ctrl:1
	s_nop 0
	v_add_f32_dpp v74, v74, v74 quad_perm:[1,0,3,2] row_mask:0xf bank_mask:0xf bound_ctrl:1
	v_add_f32_dpp v75, v75, v75 quad_perm:[1,0,3,2] row_mask:0xf bank_mask:0xf bound_ctrl:1
	s_nop 0
	v_add_f32_dpp v74, v74, v74 quad_perm:[2,3,0,1] row_mask:0xf bank_mask:0xf bound_ctrl:1
	v_add_f32_dpp v75, v75, v75 quad_perm:[2,3,0,1] row_mask:0xf bank_mask:0xf bound_ctrl:1
	s_nop 0
	v_add_f32_dpp v76, v74, v74 row_half_mirror row_mask:0xf bank_mask:0xf bound_ctrl:1
	v_add_f32_dpp v64, v75, v75 row_half_mirror row_mask:0xf bank_mask:0xf bound_ctrl:1
	s_nop 0
	v_mov_b32_dpp v77, v76 row_ror:8 row_mask:0xf bank_mask:0xf bound_ctrl:1
	s_waitcnt lgkmcnt(2)
	v_pk_mul_f32 v[66:67], v[76:77], v[56:57] op_sel_hi:[1,0]
	v_pk_mul_f32 v[68:69], v[76:77], v[56:57] op_sel:[0,1]
	v_pk_mul_f32 v[70:71], v[76:77], v[58:59] op_sel_hi:[1,0]
	v_pk_mul_f32 v[72:73], v[76:77], v[58:59] op_sel:[0,1]
	v_pk_fma_f32 v[66:67], v[60:61], v[52:53], v[66:67] op_sel_hi:[1,0,1]
	v_pk_fma_f32 v[68:69], v[60:61], v[52:53], v[68:69] op_sel:[0,1,0]
	v_pk_fma_f32 v[70:71], v[60:61], v[54:55], v[70:71] op_sel_hi:[1,0,1]
	v_pk_fma_f32 v[72:73], v[60:61], v[54:55], v[72:73] op_sel:[0,1,0]
	v_pk_fma_f32 v[0:1], v[0:1], v[48:49], v[66:67] op_sel_hi:[1,0,1]
	v_pk_fma_f32 v[2:3], v[2:3], v[48:49], v[68:69] op_sel:[0,1,0]
	v_pk_fma_f32 v[4:5], v[4:5], v[50:51], v[70:71] op_sel_hi:[1,0,1]
	v_pk_fma_f32 v[6:7], v[6:7], v[50:51], v[72:73] op_sel:[0,1,0]
	ds_write_b32 v84, v64 offset:3968
	ds_write_b32 v84, v76 offset:16256
